# de-pack v_pk_add_f32 into v_add_f32 pairs in dense attention loops
# baseline (speedup 1.0000x reference)
.LBB0_523:
	v_lshl_add_u64 v[184:185], v[170:171], 0, v[172:173]
	s_mov_b32 m0, s5
	v_lshl_add_u64 v[48:49], v[184:185], 0, s[8:9]
	v_lshl_add_u64 v[186:187], v[168:169], 0, v[172:173]
	global_load_lds_dwordx4 v[48:49], off
	v_lshl_add_u64 v[48:49], v[186:187], 0, s[10:11]
	s_mov_b32 m0, s4
	s_nop 0
	global_load_lds_dwordx4 v[48:49], off
	ds_read_b128 v[48:51], v193 offset:20480
	ds_read_b128 v[52:55], v193 offset:24576
	s_waitcnt lgkmcnt(0)
	v_mfma_f32_32x32x16_bf16 v[128:143], v[48:51], v[152:155], v[64:79]
	ds_read_b128 v[56:59], v200 offset:20480
	ds_read_b128 v[60:63], v200 offset:24576
	s_setprio 1
	v_exp_f32_e32 v174, v96
	v_exp_f32_e32 v175, v97
	v_exp_f32_e32 v176, v98
	v_exp_f32_e32 v177, v99
	s_setprio 0
	s_waitcnt lgkmcnt(0)
	v_mfma_f32_32x32x16_bf16 v[128:143], v[56:59], v[144:147], v[128:143]
	ds_read_b128 v[48:51], v201 offset:20480
	ds_read_b128 v[96:99], v201 offset:24576
	s_setprio 1
	v_mfma_f32_32x32x16_bf16 v[112:127], v[52:55], v[152:155], v[64:79]
	v_exp_f32_e32 v56, v100
	v_exp_f32_e32 v57, v101
	v_exp_f32_e32 v58, v102
	v_exp_f32_e32 v59, v103
	s_setprio 0
	v_cvt_pk_bf16_f32 v52, v174, v175
	v_cvt_pk_bf16_f32 v53, v176, v177
	v_cvt_pk_bf16_f32 v54, v56, v57
	v_cvt_pk_bf16_f32 v55, v58, v59
	s_waitcnt lgkmcnt(0)
	v_mfma_f32_32x32x16_bf16 v[128:143], v[48:51], v[148:151], v[128:143]
	ds_read_b128 v[56:59], v202 offset:20480
	ds_read_b128 v[100:103], v202 offset:24576
	s_setprio 1
	v_exp_f32_e32 v48, v104
	v_exp_f32_e32 v49, v105
	v_exp_f32_e32 v50, v106
	v_exp_f32_e32 v51, v107
	s_setprio 0
	s_waitcnt lgkmcnt(0)
	v_mfma_f32_32x32x16_bf16 v[128:143], v[56:59], v[156:159], v[128:143]
	s_setprio 1
	v_mfma_f32_32x32x16_bf16 v[112:127], v[60:63], v[144:147], v[112:127]
	v_exp_f32_e32 v56, v108
	v_exp_f32_e32 v57, v109
	v_exp_f32_e32 v58, v110
	v_exp_f32_e32 v59, v111
	v_mfma_f32_32x32x16_bf16 v[112:127], v[96:99], v[148:151], v[112:127]
	s_setprio 0
	v_cvt_pk_bf16_f32 v48, v48, v49
	v_cvt_pk_bf16_f32 v49, v50, v51
	v_cvt_pk_bf16_f32 v50, v56, v57
	v_cvt_pk_bf16_f32 v51, v58, v59
	ds_read_b128 v[56:59], v205 offset:8192
	ds_read_b128 v[60:63], v205 offset:12288
	s_waitcnt lgkmcnt(0)
	v_mfma_f32_32x32x16_bf16 v[0:15], v[60:63], v[52:55], v[0:15]
	ds_read_b128 v[96:99], v204 offset:8192
	ds_read_b128 v[104:107], v204 offset:12288
	s_setprio 1
	v_mfma_f32_32x32x16_bf16 v[32:47], v[56:59], v[52:55], v[32:47]
	v_exp_f32_e32 v108, v80
	v_exp_f32_e32 v111, v81
	v_exp_f32_e32 v110, v82
	v_exp_f32_e32 v109, v83
	s_setprio 0
	s_setprio 1
	v_exp_f32_e32 v84, v84
	v_exp_f32_e32 v175, v85
	v_exp_f32_e32 v174, v86
	v_exp_f32_e32 v85, v87
	s_setprio 0
	v_cvt_pk_bf16_f32 v56, v108, v111
	v_cvt_pk_bf16_f32 v57, v110, v109
	v_cvt_pk_bf16_f32 v58, v84, v175
	v_cvt_pk_bf16_f32 v59, v174, v85
	s_waitcnt lgkmcnt(0)
	v_mfma_f32_32x32x16_bf16 v[0:15], v[104:107], v[48:51], v[0:15]
	ds_read_b128 v[60:63], v203 offset:8192
	ds_read_b128 v[80:83], v203 offset:12288
	s_setprio 1
	v_mfma_f32_32x32x16_bf16 v[112:127], v[100:103], v[156:159], v[112:127]
	v_exp_f32_e32 v88, v88
	v_exp_f32_e32 v105, v89
	v_exp_f32_e32 v104, v90
	v_exp_f32_e32 v89, v91
	v_add_f32_e32 v86, v188, v110
	v_add_f32_e32 v87, v189, v111
	v_add_f32_e32 v90, v190, v108
	v_add_f32_e32 v91, v191, v109
	v_add_f32_e32 v86, v174, v86
	v_add_f32_e32 v87, v175, v87
	v_mfma_f32_32x32x16_bf16 v[32:47], v[96:99], v[48:51], v[32:47]
	v_add_f32_e64 v84, v84, v90
	v_add_f32_e64 v85, v85, v91
	v_add_f32_e64 v86, v104, v86
	v_add_f32_e64 v87, v105, v87
	v_add_f32_e64 v84, v88, v84
	v_add_f32_e64 v85, v89, v85
	s_setprio 0
	s_setprio 1
	v_exp_f32_e32 v90, v92
	v_exp_f32_e32 v93, v93
	v_exp_f32_e32 v92, v94
	v_exp_f32_e32 v91, v95
	v_add_f32_e32 v190, v92, v86
	v_add_f32_e32 v191, v93, v87
	v_add_f32_e32 v188, v90, v84
	v_add_f32_e32 v189, v91, v85
	v_mov_b64_e32 v[86:87], s[38:39]
	v_mov_b64_e32 v[84:85], s[36:37]
	s_nop 1
	v_mfma_f32_32x32x16_bf16 v[16:31], v[84:87], v[52:55], v[16:31]
	v_mfma_f32_32x32x16_bf16 v[16:31], v[84:87], v[48:51], v[16:31]
	s_setprio 0
	v_cvt_pk_bf16_f32 v48, v88, v105
	v_cvt_pk_bf16_f32 v49, v104, v89
	v_cvt_pk_bf16_f32 v50, v90, v93
	v_cvt_pk_bf16_f32 v51, v92, v91
	s_waitcnt lgkmcnt(0)
	v_mfma_f32_32x32x16_bf16 v[32:47], v[60:63], v[56:59], v[32:47]
	ds_read_b128 v[52:55], v192 offset:8192
	ds_read_b128 v[84:87], v192 offset:12288
	v_mfma_f32_32x32x16_bf16 v[0:15], v[80:83], v[56:59], v[0:15]
	v_max_f32_e32 v56, v128, v128
	v_max_f32_e32 v56, 0xf149f2ca, v56
	v_max3_f32 v57, v130, s72, v131
	v_max3_f32 v56, v56, v129, v132
	v_max3_f32 v57, v57, v134, v135
	v_max3_f32 v56, v56, v133, v136
	v_max3_f32 v57, v57, v138, v139
	v_max3_f32 v56, v56, v137, v140
	v_max3_f32 v57, v57, v142, v143
	s_waitcnt lgkmcnt(0)
	v_mfma_f32_32x32x16_bf16 v[32:47], v[52:55], v[48:51], v[32:47]
	v_max3_f32 v52, v56, v141, v112
	v_max3_f32 v53, v57, v114, v115
	v_max3_f32 v52, v52, v113, v116
	v_max3_f32 v53, v53, v118, v119
	v_max3_f32 v52, v52, v117, v120
	v_max3_f32 v53, v53, v122, v123
	v_max3_f32 v52, v52, v121, v124
	v_mfma_f32_32x32x16_bf16 v[0:15], v[84:87], v[48:51], v[0:15]
	v_max3_f32 v53, v53, v126, v127
	v_max3_f32 v48, v52, v125, v53
	v_mov_b32_e32 v49, v48
	s_nop 1
	v_permlane32_swap_b32_e32 v48, v49
	s_waitcnt vmcnt(2)
	v_max_f32_e32 v49, v49, v49
	v_max_f32_e32 v48, v48, v48
	s_waitcnt lgkmcnt(0)
	s_barrier
	v_max_f32_e32 v48, v48, v49
	v_cmp_lt_f32_e32 vcc, s96, v48
	s_cbranch_vccz .LBB0_525
	v_max_f32_e32 v48, v48, v48
	v_max_f32_e32 v50, 0, v48
	v_exp_f32_e64 v52, -v50
	v_add_f32_e32 v206, v206, v50
	v_xor_b32_e32 v48, 0x80000000, v206
	v_pk_add_f32 v[128:129], v[128:129], v[50:51] op_sel_hi:[1,0] neg_lo:[0,1] neg_hi:[0,1]
	v_pk_add_f32 v[112:113], v[112:113], v[50:51] op_sel_hi:[1,0] neg_lo:[0,1] neg_hi:[0,1]
	v_pk_add_f32 v[130:131], v[130:131], v[50:51] op_sel_hi:[1,0] neg_lo:[0,1] neg_hi:[0,1]
	v_pk_add_f32 v[114:115], v[114:115], v[50:51] op_sel_hi:[1,0] neg_lo:[0,1] neg_hi:[0,1]
	v_pk_add_f32 v[132:133], v[132:133], v[50:51] op_sel_hi:[1,0] neg_lo:[0,1] neg_hi:[0,1]
	v_pk_add_f32 v[116:117], v[116:117], v[50:51] op_sel_hi:[1,0] neg_lo:[0,1] neg_hi:[0,1]
	v_pk_add_f32 v[134:135], v[134:135], v[50:51] op_sel_hi:[1,0] neg_lo:[0,1] neg_hi:[0,1]
	v_pk_add_f32 v[118:119], v[118:119], v[50:51] op_sel_hi:[1,0] neg_lo:[0,1] neg_hi:[0,1]
	v_pk_add_f32 v[136:137], v[136:137], v[50:51] op_sel_hi:[1,0] neg_lo:[0,1] neg_hi:[0,1]
	v_pk_add_f32 v[120:121], v[120:121], v[50:51] op_sel_hi:[1,0] neg_lo:[0,1] neg_hi:[0,1]
	v_pk_add_f32 v[138:139], v[138:139], v[50:51] op_sel_hi:[1,0] neg_lo:[0,1] neg_hi:[0,1]
	v_pk_add_f32 v[122:123], v[122:123], v[50:51] op_sel_hi:[1,0] neg_lo:[0,1] neg_hi:[0,1]
	v_pk_add_f32 v[140:141], v[140:141], v[50:51] op_sel_hi:[1,0] neg_lo:[0,1] neg_hi:[0,1]
	v_pk_add_f32 v[124:125], v[124:125], v[50:51] op_sel_hi:[1,0] neg_lo:[0,1] neg_hi:[0,1]
	v_pk_add_f32 v[142:143], v[142:143], v[50:51] op_sel_hi:[1,0] neg_lo:[0,1] neg_hi:[0,1]
	v_pk_add_f32 v[126:127], v[126:127], v[50:51] op_sel_hi:[1,0] neg_lo:[0,1] neg_hi:[0,1]
	v_pk_mul_f32 v[46:47], v[46:47], v[52:53] op_sel_hi:[1,0]
	v_pk_mul_f32 v[44:45], v[44:45], v[52:53] op_sel_hi:[1,0]
	v_pk_mul_f32 v[42:43], v[42:43], v[52:53] op_sel_hi:[1,0]
	v_pk_mul_f32 v[40:41], v[40:41], v[52:53] op_sel_hi:[1,0]
	v_pk_mul_f32 v[38:39], v[38:39], v[52:53] op_sel_hi:[1,0]
	v_pk_mul_f32 v[36:37], v[36:37], v[52:53] op_sel_hi:[1,0]
	v_pk_mul_f32 v[34:35], v[34:35], v[52:53] op_sel_hi:[1,0]
	v_pk_mul_f32 v[32:33], v[32:33], v[52:53] op_sel_hi:[1,0]
	v_pk_mul_f32 v[14:15], v[14:15], v[52:53] op_sel_hi:[1,0]
	v_pk_mul_f32 v[12:13], v[12:13], v[52:53] op_sel_hi:[1,0]
	v_pk_mul_f32 v[10:11], v[10:11], v[52:53] op_sel_hi:[1,0]
	v_pk_mul_f32 v[8:9], v[8:9], v[52:53] op_sel_hi:[1,0]
	v_pk_mul_f32 v[6:7], v[6:7], v[52:53] op_sel_hi:[1,0]
	v_pk_mul_f32 v[4:5], v[4:5], v[52:53] op_sel_hi:[1,0]
	v_pk_mul_f32 v[2:3], v[2:3], v[52:53] op_sel_hi:[1,0]
	v_pk_mul_f32 v[0:1], v[0:1], v[52:53] op_sel_hi:[1,0]
	v_pk_mul_f32 v[30:31], v[30:31], v[52:53] op_sel_hi:[1,0]
	v_pk_mul_f32 v[28:29], v[28:29], v[52:53] op_sel_hi:[1,0]
	v_pk_mul_f32 v[26:27], v[26:27], v[52:53] op_sel_hi:[1,0]
	v_pk_mul_f32 v[24:25], v[24:25], v[52:53] op_sel_hi:[1,0]
	v_pk_mul_f32 v[22:23], v[22:23], v[52:53] op_sel_hi:[1,0]
	v_pk_mul_f32 v[20:21], v[20:21], v[52:53] op_sel_hi:[1,0]
	v_pk_mul_f32 v[18:19], v[18:19], v[52:53] op_sel_hi:[1,0]
	v_pk_mul_f32 v[16:17], v[16:17], v[52:53] op_sel_hi:[1,0]
	v_pk_mul_f32 v[188:189], v[188:189], v[52:53] op_sel_hi:[1,0]
	v_pk_mul_f32 v[190:191], v[190:191], v[52:53] op_sel_hi:[1,0]
	v_mov_b32_e32 v49, v48
	v_mov_b32_e32 v50, v48
	v_mov_b32_e32 v51, v48
	v_mov_b32_e32 v52, v48
	v_mov_b32_e32 v53, v48
	v_mov_b32_e32 v54, v48
	v_mov_b32_e32 v55, v48
	v_mov_b32_e32 v56, v48
	v_mov_b32_e32 v57, v48
	v_mov_b32_e32 v58, v48
	v_mov_b32_e32 v59, v48
	v_mov_b32_e32 v60, v48
	v_mov_b32_e32 v61, v48
	v_mov_b32_e32 v62, v48
	v_mov_b32_e32 v63, v48
	v_mov_b32_e32 v64, v48
	v_mov_b32_e32 v65, v48
	v_mov_b32_e32 v66, v48
	v_mov_b32_e32 v67, v48
	v_mov_b32_e32 v68, v48
	v_mov_b32_e32 v69, v48
	v_mov_b32_e32 v70, v48
	v_mov_b32_e32 v71, v48
	v_mov_b32_e32 v72, v48
	v_mov_b32_e32 v73, v48
	v_mov_b32_e32 v74, v48
	v_mov_b32_e32 v75, v48
	v_mov_b32_e32 v76, v48
	v_mov_b32_e32 v77, v48
	v_mov_b32_e32 v78, v48
	v_mov_b32_e32 v79, v48
	s_branch .LBB0_526

.LBB0_526:
	s_mov_b64 s[8:9], 0x31da200
	s_mov_b32 m0, s46
	v_lshl_add_u64 v[80:81], v[184:185], 0, s[8:9]
	s_mov_b64 s[8:9], 0x17618200
	global_load_lds_dwordx4 v[80:81], off
	v_lshl_add_u64 v[80:81], v[186:187], 0, s[8:9]
	s_mov_b32 m0, s47
	s_nop 0
	global_load_lds_dwordx4 v[80:81], off
	ds_read_b128 v[80:83], v193 offset:40960
	ds_read_b128 v[174:177], v193 offset:45056
	s_waitcnt lgkmcnt(0)
	v_mfma_f32_32x32x16_bf16 v[96:111], v[80:83], v[152:155], v[48:63]
	ds_read_b128 v[84:87], v200 offset:40960
	ds_read_b128 v[180:183], v200 offset:45056
	s_setprio 1
	v_exp_f32_e32 v194, v128
	v_exp_f32_e32 v195, v129
	v_exp_f32_e32 v215, v130
	v_exp_f32_e32 v220, v131
	s_setprio 0
	s_waitcnt lgkmcnt(0)
	v_mfma_f32_32x32x16_bf16 v[96:111], v[84:87], v[144:147], v[96:111]
	ds_read_b128 v[128:131], v201 offset:40960
	ds_read_b128 v[216:219], v201 offset:45056
	s_setprio 1
	v_mfma_f32_32x32x16_bf16 v[80:95], v[174:177], v[152:155], v[48:63]
	v_exp_f32_e32 v221, v132
	v_exp_f32_e32 v222, v133
	v_exp_f32_e32 v223, v134
	v_exp_f32_e32 v135, v135
	s_setprio 0
	v_cvt_pk_bf16_f32 v132, v194, v195
	v_cvt_pk_bf16_f32 v133, v215, v220
	v_cvt_pk_bf16_f32 v134, v221, v222
	v_cvt_pk_bf16_f32 v135, v223, v135
	s_waitcnt lgkmcnt(0)
	v_mfma_f32_32x32x16_bf16 v[96:111], v[128:131], v[148:151], v[96:111]
	ds_read_b128 v[174:177], v202 offset:40960
	ds_read_b128 v[220:223], v202 offset:45056
	s_setprio 1
	v_exp_f32_e32 v128, v136
	v_exp_f32_e32 v129, v137
	v_exp_f32_e32 v130, v138
	v_exp_f32_e32 v131, v139
	s_setprio 0
	s_waitcnt lgkmcnt(0)
	v_mfma_f32_32x32x16_bf16 v[96:111], v[174:177], v[156:159], v[96:111]
	s_setprio 1
	v_mfma_f32_32x32x16_bf16 v[80:95], v[180:183], v[144:147], v[80:95]
	v_exp_f32_e32 v136, v140
	v_exp_f32_e32 v137, v141
	v_exp_f32_e32 v138, v142
	v_exp_f32_e32 v139, v143
	v_mfma_f32_32x32x16_bf16 v[80:95], v[216:219], v[148:151], v[80:95]
	s_setprio 0
	v_cvt_pk_bf16_f32 v128, v128, v129
	v_cvt_pk_bf16_f32 v129, v130, v131
	v_cvt_pk_bf16_f32 v130, v136, v137
	v_cvt_pk_bf16_f32 v131, v138, v139
	ds_read_b128 v[136:139], v205 offset:28672
	ds_read_b128 v[140:143], v205 offset:32768
	s_waitcnt lgkmcnt(0)
	v_mfma_f32_32x32x16_bf16 v[0:15], v[140:143], v[132:135], v[0:15]
	ds_read_b128 v[174:177], v204 offset:28672
	ds_read_b128 v[180:183], v204 offset:32768
	s_setprio 1
	v_mfma_f32_32x32x16_bf16 v[32:47], v[136:139], v[132:135], v[32:47]
	v_exp_f32_e32 v140, v112
	v_exp_f32_e32 v143, v113
	v_exp_f32_e32 v142, v114
	v_exp_f32_e32 v141, v115
	s_setprio 0
	s_setprio 1
	v_exp_f32_e32 v194, v116
	v_exp_f32_e32 v217, v117
	v_exp_f32_e32 v216, v118
	v_exp_f32_e32 v195, v119
	s_setprio 0
	v_cvt_pk_bf16_f32 v112, v140, v143
	v_cvt_pk_bf16_f32 v113, v142, v141
	v_cvt_pk_bf16_f32 v114, v194, v217
	v_cvt_pk_bf16_f32 v115, v216, v195
	s_waitcnt lgkmcnt(0)
	v_mfma_f32_32x32x16_bf16 v[0:15], v[180:183], v[128:131], v[0:15]
	ds_read_b128 v[116:119], v203 offset:28672
	ds_read_b128 v[136:139], v203 offset:32768
	s_setprio 1
	v_mfma_f32_32x32x16_bf16 v[80:95], v[220:223], v[156:159], v[80:95]
	v_exp_f32_e32 v180, v120
	v_exp_f32_e32 v183, v121
	v_exp_f32_e32 v182, v122
	v_exp_f32_e32 v181, v123
	v_add_f32_e32 v120, v142, v190
	v_add_f32_e32 v121, v143, v191
	v_add_f32_e32 v122, v140, v188
	v_add_f32_e32 v123, v141, v189
	v_add_f32_e32 v120, v216, v120
	v_add_f32_e32 v121, v217, v121
	v_mfma_f32_32x32x16_bf16 v[32:47], v[174:177], v[128:131], v[32:47]
	v_add_f32_e64 v122, v194, v122
	v_add_f32_e64 v123, v195, v123
	v_add_f32_e64 v120, v182, v120
	v_add_f32_e64 v121, v183, v121
	v_add_f32_e64 v122, v180, v122
	v_add_f32_e64 v123, v181, v123
	s_setprio 0
	s_setprio 1
	v_exp_f32_e32 v124, v124
	v_exp_f32_e32 v141, v125
	v_exp_f32_e32 v140, v126
	v_exp_f32_e32 v125, v127
	v_add_f32_e32 v188, v140, v120
	v_add_f32_e32 v189, v141, v121
	v_add_f32_e32 v190, v124, v122
	v_add_f32_e32 v191, v125, v123
	v_mov_b64_e32 v[122:123], s[38:39]
	v_mov_b64_e32 v[120:121], s[36:37]
	s_nop 1
	v_mfma_f32_32x32x16_bf16 v[16:31], v[120:123], v[132:135], v[16:31]
	v_mfma_f32_32x32x16_bf16 v[16:31], v[120:123], v[128:131], v[16:31]
	s_setprio 0
	v_cvt_pk_bf16_f32 v120, v180, v183
	v_cvt_pk_bf16_f32 v121, v182, v181
	v_cvt_pk_bf16_f32 v122, v124, v141
	v_cvt_pk_bf16_f32 v123, v140, v125
	s_waitcnt lgkmcnt(0)
	v_mfma_f32_32x32x16_bf16 v[32:47], v[116:119], v[112:115], v[32:47]
	ds_read_b128 v[124:127], v192 offset:28672
	ds_read_b128 v[128:131], v192 offset:32768
	v_mfma_f32_32x32x16_bf16 v[0:15], v[136:139], v[112:115], v[0:15]
	v_max_f32_e32 v112, v96, v96
	v_max_f32_e32 v112, 0xf149f2ca, v112
	v_max3_f32 v113, v98, s72, v99
	v_max3_f32 v112, v112, v97, v100
	v_max3_f32 v113, v113, v102, v103
	v_max3_f32 v112, v112, v101, v104
	v_max3_f32 v113, v113, v106, v107
	v_max3_f32 v112, v112, v105, v108
	v_max3_f32 v113, v113, v110, v111
	s_waitcnt lgkmcnt(0)
	v_mfma_f32_32x32x16_bf16 v[32:47], v[124:127], v[120:123], v[32:47]
	v_max3_f32 v112, v112, v109, v80
	v_max3_f32 v113, v113, v82, v83
	v_max3_f32 v112, v112, v81, v84
	v_max3_f32 v113, v113, v86, v87
	v_max3_f32 v112, v112, v85, v88
	v_max3_f32 v113, v113, v90, v91
	v_max3_f32 v112, v112, v89, v92
	v_mfma_f32_32x32x16_bf16 v[0:15], v[128:131], v[120:123], v[0:15]
	v_max3_f32 v113, v113, v94, v95
	v_max3_f32 v112, v112, v93, v113
	v_mov_b32_e32 v113, v112
	s_nop 1
	v_permlane32_swap_b32_e32 v112, v113
	s_waitcnt vmcnt(2)
	v_max_f32_e32 v113, v113, v113
	v_max_f32_e32 v112, v112, v112
	s_waitcnt lgkmcnt(0)
	s_barrier
	v_max_f32_e32 v112, v112, v113
	v_cmp_lt_f32_e32 vcc, s96, v112
	s_cbranch_vccz .LBB0_528
	v_max_f32_e32 v48, v112, v112
	v_max_f32_e32 v50, 0, v48
	v_exp_f32_e64 v52, -v50
	v_add_f32_e32 v206, v206, v50
	v_xor_b32_e32 v48, 0x80000000, v206
	v_pk_add_f32 v[96:97], v[96:97], v[50:51] op_sel_hi:[1,0] neg_lo:[0,1] neg_hi:[0,1]
	v_pk_add_f32 v[80:81], v[80:81], v[50:51] op_sel_hi:[1,0] neg_lo:[0,1] neg_hi:[0,1]
	v_pk_add_f32 v[98:99], v[98:99], v[50:51] op_sel_hi:[1,0] neg_lo:[0,1] neg_hi:[0,1]
	v_pk_add_f32 v[82:83], v[82:83], v[50:51] op_sel_hi:[1,0] neg_lo:[0,1] neg_hi:[0,1]
	v_pk_add_f32 v[100:101], v[100:101], v[50:51] op_sel_hi:[1,0] neg_lo:[0,1] neg_hi:[0,1]
	v_pk_add_f32 v[84:85], v[84:85], v[50:51] op_sel_hi:[1,0] neg_lo:[0,1] neg_hi:[0,1]
	v_pk_add_f32 v[102:103], v[102:103], v[50:51] op_sel_hi:[1,0] neg_lo:[0,1] neg_hi:[0,1]
	v_pk_add_f32 v[86:87], v[86:87], v[50:51] op_sel_hi:[1,0] neg_lo:[0,1] neg_hi:[0,1]
	v_pk_add_f32 v[104:105], v[104:105], v[50:51] op_sel_hi:[1,0] neg_lo:[0,1] neg_hi:[0,1]
	v_pk_add_f32 v[88:89], v[88:89], v[50:51] op_sel_hi:[1,0] neg_lo:[0,1] neg_hi:[0,1]
	v_pk_add_f32 v[106:107], v[106:107], v[50:51] op_sel_hi:[1,0] neg_lo:[0,1] neg_hi:[0,1]
	v_pk_add_f32 v[90:91], v[90:91], v[50:51] op_sel_hi:[1,0] neg_lo:[0,1] neg_hi:[0,1]
	v_pk_add_f32 v[108:109], v[108:109], v[50:51] op_sel_hi:[1,0] neg_lo:[0,1] neg_hi:[0,1]
	v_pk_add_f32 v[92:93], v[92:93], v[50:51] op_sel_hi:[1,0] neg_lo:[0,1] neg_hi:[0,1]
	v_pk_add_f32 v[110:111], v[110:111], v[50:51] op_sel_hi:[1,0] neg_lo:[0,1] neg_hi:[0,1]
	v_pk_add_f32 v[94:95], v[94:95], v[50:51] op_sel_hi:[1,0] neg_lo:[0,1] neg_hi:[0,1]
	v_pk_mul_f32 v[46:47], v[46:47], v[52:53] op_sel_hi:[1,0]
	v_pk_mul_f32 v[44:45], v[44:45], v[52:53] op_sel_hi:[1,0]
	v_pk_mul_f32 v[42:43], v[42:43], v[52:53] op_sel_hi:[1,0]
	v_pk_mul_f32 v[40:41], v[40:41], v[52:53] op_sel_hi:[1,0]
	v_pk_mul_f32 v[38:39], v[38:39], v[52:53] op_sel_hi:[1,0]
	v_pk_mul_f32 v[36:37], v[36:37], v[52:53] op_sel_hi:[1,0]
	v_pk_mul_f32 v[34:35], v[34:35], v[52:53] op_sel_hi:[1,0]
	v_pk_mul_f32 v[32:33], v[32:33], v[52:53] op_sel_hi:[1,0]
	v_pk_mul_f32 v[14:15], v[14:15], v[52:53] op_sel_hi:[1,0]
	v_pk_mul_f32 v[12:13], v[12:13], v[52:53] op_sel_hi:[1,0]
	v_pk_mul_f32 v[10:11], v[10:11], v[52:53] op_sel_hi:[1,0]
	v_pk_mul_f32 v[8:9], v[8:9], v[52:53] op_sel_hi:[1,0]
	v_pk_mul_f32 v[6:7], v[6:7], v[52:53] op_sel_hi:[1,0]
	v_pk_mul_f32 v[4:5], v[4:5], v[52:53] op_sel_hi:[1,0]
	v_pk_mul_f32 v[2:3], v[2:3], v[52:53] op_sel_hi:[1,0]
	v_pk_mul_f32 v[0:1], v[0:1], v[52:53] op_sel_hi:[1,0]
	v_pk_mul_f32 v[30:31], v[30:31], v[52:53] op_sel_hi:[1,0]
	v_pk_mul_f32 v[28:29], v[28:29], v[52:53] op_sel_hi:[1,0]
	v_pk_mul_f32 v[26:27], v[26:27], v[52:53] op_sel_hi:[1,0]
	v_pk_mul_f32 v[24:25], v[24:25], v[52:53] op_sel_hi:[1,0]
	v_pk_mul_f32 v[22:23], v[22:23], v[52:53] op_sel_hi:[1,0]
	v_pk_mul_f32 v[20:21], v[20:21], v[52:53] op_sel_hi:[1,0]
	v_pk_mul_f32 v[18:19], v[18:19], v[52:53] op_sel_hi:[1,0]
	v_pk_mul_f32 v[16:17], v[16:17], v[52:53] op_sel_hi:[1,0]
	v_pk_mul_f32 v[190:191], v[190:191], v[52:53] op_sel_hi:[1,0]
	v_pk_mul_f32 v[188:189], v[188:189], v[52:53] op_sel_hi:[1,0]
	v_mov_b32_e32 v49, v48
	v_mov_b32_e32 v50, v48
	v_mov_b32_e32 v51, v48
	v_mov_b32_e32 v52, v48
	v_mov_b32_e32 v53, v48
	v_mov_b32_e32 v54, v48
	v_mov_b32_e32 v55, v48
	v_mov_b32_e32 v56, v48
	v_mov_b32_e32 v57, v48
	v_mov_b32_e32 v58, v48
	v_mov_b32_e32 v59, v48
	v_mov_b32_e32 v60, v48
	v_mov_b32_e32 v61, v48
	v_mov_b32_e32 v62, v48
	v_mov_b32_e32 v63, v48
	v_mov_b32_e32 v64, v48
	v_mov_b32_e32 v65, v48
	v_mov_b32_e32 v66, v48
	v_mov_b32_e32 v67, v48
	v_mov_b32_e32 v68, v48
	v_mov_b32_e32 v69, v48
	v_mov_b32_e32 v70, v48
	v_mov_b32_e32 v71, v48
	v_mov_b32_e32 v72, v48
	v_mov_b32_e32 v73, v48
	v_mov_b32_e32 v74, v48
	v_mov_b32_e32 v75, v48
	v_mov_b32_e32 v76, v48
	v_mov_b32_e32 v77, v48
	v_mov_b32_e32 v78, v48
	v_mov_b32_e32 v79, v48
.LBB0_528:
	s_mov_b32 m0, s70
	v_lshl_add_u64 v[112:113], v[184:185], 0, s[12:13]
	global_load_lds_dwordx4 v[112:113], off
	v_lshl_add_u64 v[112:113], v[186:187], 0, s[14:15]
	s_mov_b32 m0, s71
	s_add_i32 s7, 0, 0x10000
	global_load_lds_dwordx4 v[112:113], off
	v_add_u32_e32 v215, s7, v207
	ds_read_b128 v[112:115], v193 offset:61440
	ds_read_b128 v[174:177], v215
	s_waitcnt lgkmcnt(0)
	v_mfma_f32_32x32x16_bf16 v[128:143], v[112:115], v[152:155], v[48:63]
	v_add_u32_e32 v216, s7, v208
	ds_read_b128 v[116:119], v200 offset:61440
	ds_read_b128 v[180:183], v216
	s_setprio 1
	v_exp_f32_e32 v218, v98
	v_exp_f32_e32 v194, v96
	v_exp_f32_e32 v195, v97
	v_exp_f32_e32 v219, v99
	s_setprio 0
	s_waitcnt lgkmcnt(0)
	v_mfma_f32_32x32x16_bf16 v[128:143], v[116:119], v[144:147], v[128:143]
	v_add_u32_e32 v217, s7, v210
	ds_read_b128 v[96:99], v201 offset:61440
	ds_read_b128 v[220:223], v217
	s_setprio 1
	v_mfma_f32_32x32x16_bf16 v[112:127], v[174:177], v[152:155], v[48:63]
	v_exp_f32_e32 v224, v100
	v_exp_f32_e32 v225, v101
	v_exp_f32_e32 v226, v102
	v_exp_f32_e32 v103, v103
	s_setprio 0
	v_cvt_pk_bf16_f32 v100, v194, v195
	v_cvt_pk_bf16_f32 v101, v218, v219
	v_cvt_pk_bf16_f32 v102, v224, v225
	v_cvt_pk_bf16_f32 v103, v226, v103
	s_waitcnt lgkmcnt(0)
	v_mfma_f32_32x32x16_bf16 v[128:143], v[96:99], v[148:151], v[128:143]
	v_add_u32_e32 v218, s7, v213
	ds_read_b128 v[174:177], v202 offset:61440
	ds_read_b128 v[224:227], v218
	s_setprio 1
	v_exp_f32_e32 v96, v104
	v_exp_f32_e32 v97, v105
	v_exp_f32_e32 v98, v106
	v_exp_f32_e32 v99, v107
	s_setprio 0
	s_waitcnt lgkmcnt(0)
	v_mfma_f32_32x32x16_bf16 v[128:143], v[174:177], v[156:159], v[128:143]
	s_setprio 1
	v_mfma_f32_32x32x16_bf16 v[112:127], v[180:183], v[144:147], v[112:127]
	v_exp_f32_e32 v104, v108
	v_exp_f32_e32 v105, v109
	v_exp_f32_e32 v106, v110
	v_exp_f32_e32 v107, v111
	v_mfma_f32_32x32x16_bf16 v[112:127], v[220:223], v[148:151], v[112:127]
	s_setprio 0
	v_cvt_pk_bf16_f32 v96, v96, v97
	v_cvt_pk_bf16_f32 v97, v98, v99
	v_cvt_pk_bf16_f32 v98, v104, v105
	v_cvt_pk_bf16_f32 v99, v106, v107
	ds_read_b128 v[104:107], v205 offset:49152
	ds_read_b128 v[108:111], v205 offset:53248
	s_waitcnt lgkmcnt(0)
	v_mfma_f32_32x32x16_bf16 v[0:15], v[108:111], v[100:103], v[0:15]
	ds_read_b128 v[174:177], v204 offset:49152
	ds_read_b128 v[180:183], v204 offset:53248
	s_setprio 1
	v_mfma_f32_32x32x16_bf16 v[32:47], v[104:107], v[100:103], v[32:47]
	v_exp_f32_e32 v108, v80
	v_exp_f32_e32 v111, v81
	v_exp_f32_e32 v110, v82
	v_exp_f32_e32 v109, v83
	s_setprio 0
	s_setprio 1
	v_exp_f32_e32 v194, v84
	v_exp_f32_e32 v221, v85
	v_exp_f32_e32 v220, v86
	v_exp_f32_e32 v195, v87
	s_setprio 0
	v_cvt_pk_bf16_f32 v80, v108, v111
	v_cvt_pk_bf16_f32 v81, v110, v109
	v_cvt_pk_bf16_f32 v82, v194, v221
	v_cvt_pk_bf16_f32 v83, v220, v195
	s_waitcnt lgkmcnt(0)
	v_mfma_f32_32x32x16_bf16 v[0:15], v[180:183], v[96:99], v[0:15]
	ds_read_b128 v[84:87], v203 offset:49152
	ds_read_b128 v[104:107], v203 offset:53248
	s_setprio 1
	v_mfma_f32_32x32x16_bf16 v[112:127], v[224:227], v[156:159], v[112:127]
	v_exp_f32_e32 v180, v88
	v_exp_f32_e32 v183, v89
	v_exp_f32_e32 v182, v90
	v_exp_f32_e32 v181, v91
	v_mfma_f32_32x32x16_bf16 v[32:47], v[174:177], v[96:99], v[32:47]
	s_setprio 0
	s_setprio 1
	v_exp_f32_e32 v175, v93
	v_exp_f32_e32 v174, v94
	v_add_f32_e32 v88, v110, v188
	v_add_f32_e32 v89, v111, v189
	v_exp_f32_e32 v92, v92
	v_add_f32_e32 v88, v220, v88
	v_add_f32_e32 v89, v221, v89
	v_exp_f32_e32 v93, v95
	v_add_f32_e32 v88, v182, v88
	v_add_f32_e32 v89, v183, v89
	v_add_f32_e32 v188, v174, v88
	v_add_f32_e32 v189, v175, v89
	v_add_f32_e32 v88, v108, v190
	v_add_f32_e32 v89, v109, v191
	v_add_f32_e32 v88, v194, v88
	v_add_f32_e32 v89, v195, v89
	v_add_f32_e32 v88, v180, v88
	v_add_f32_e32 v89, v181, v89
	v_add_f32_e32 v190, v92, v88
	v_add_f32_e32 v191, v93, v89
	v_mov_b64_e32 v[90:91], s[38:39]
	v_mov_b64_e32 v[88:89], s[36:37]
	s_nop 1
	v_mfma_f32_32x32x16_bf16 v[16:31], v[88:91], v[100:103], v[16:31]
	v_mfma_f32_32x32x16_bf16 v[16:31], v[88:91], v[96:99], v[16:31]
	s_setprio 0
	v_cvt_pk_bf16_f32 v88, v180, v183
	v_cvt_pk_bf16_f32 v89, v182, v181
	v_cvt_pk_bf16_f32 v90, v92, v175
	v_cvt_pk_bf16_f32 v91, v174, v93
	s_waitcnt lgkmcnt(0)
	v_mfma_f32_32x32x16_bf16 v[32:47], v[84:87], v[80:83], v[32:47]
	ds_read_b128 v[92:95], v192 offset:49152
	ds_read_b128 v[96:99], v192 offset:53248
	v_mfma_f32_32x32x16_bf16 v[0:15], v[104:107], v[80:83], v[0:15]
	v_max_f32_e32 v80, v128, v128
	v_max_f32_e32 v80, 0xf149f2ca, v80
	v_max3_f32 v81, v130, s72, v131
	v_max3_f32 v80, v80, v129, v132
	v_max3_f32 v81, v81, v134, v135
	v_max3_f32 v80, v80, v133, v136
	v_max3_f32 v81, v81, v138, v139
	v_max3_f32 v80, v80, v137, v140
	v_max3_f32 v81, v81, v142, v143
	s_waitcnt lgkmcnt(0)
	v_mfma_f32_32x32x16_bf16 v[32:47], v[92:95], v[88:91], v[32:47]
	v_max3_f32 v80, v80, v141, v112
	v_max3_f32 v81, v81, v114, v115
	v_max3_f32 v80, v80, v113, v116
	v_max3_f32 v81, v81, v118, v119
	v_max3_f32 v80, v80, v117, v120
	v_max3_f32 v81, v81, v122, v123
	v_max3_f32 v80, v80, v121, v124
	v_mfma_f32_32x32x16_bf16 v[0:15], v[96:99], v[88:91], v[0:15]
	v_max3_f32 v81, v81, v126, v127
	v_max3_f32 v80, v80, v125, v81
	v_mov_b32_e32 v81, v80
	s_nop 1
	v_permlane32_swap_b32_e32 v80, v81
	s_waitcnt vmcnt(2)
	v_max_f32_e32 v81, v81, v81
	v_max_f32_e32 v80, v80, v80
	s_waitcnt lgkmcnt(0)
	s_barrier
	v_max_f32_e32 v80, v80, v81
	v_cmp_lt_f32_e32 vcc, s96, v80
	s_cbranch_vccz .LBB0_530
	v_max_f32_e32 v48, v80, v80
	v_max_f32_e32 v50, 0, v48
	v_exp_f32_e64 v52, -v50
	v_add_f32_e32 v206, v206, v50
	v_xor_b32_e32 v48, 0x80000000, v206
	v_pk_add_f32 v[128:129], v[128:129], v[50:51] op_sel_hi:[1,0] neg_lo:[0,1] neg_hi:[0,1]
	v_pk_add_f32 v[112:113], v[112:113], v[50:51] op_sel_hi:[1,0] neg_lo:[0,1] neg_hi:[0,1]
	v_pk_add_f32 v[130:131], v[130:131], v[50:51] op_sel_hi:[1,0] neg_lo:[0,1] neg_hi:[0,1]
	v_pk_add_f32 v[114:115], v[114:115], v[50:51] op_sel_hi:[1,0] neg_lo:[0,1] neg_hi:[0,1]
	v_pk_add_f32 v[132:133], v[132:133], v[50:51] op_sel_hi:[1,0] neg_lo:[0,1] neg_hi:[0,1]
	v_pk_add_f32 v[116:117], v[116:117], v[50:51] op_sel_hi:[1,0] neg_lo:[0,1] neg_hi:[0,1]
	v_pk_add_f32 v[134:135], v[134:135], v[50:51] op_sel_hi:[1,0] neg_lo:[0,1] neg_hi:[0,1]
	v_pk_add_f32 v[118:119], v[118:119], v[50:51] op_sel_hi:[1,0] neg_lo:[0,1] neg_hi:[0,1]
	v_pk_add_f32 v[136:137], v[136:137], v[50:51] op_sel_hi:[1,0] neg_lo:[0,1] neg_hi:[0,1]
	v_pk_add_f32 v[120:121], v[120:121], v[50:51] op_sel_hi:[1,0] neg_lo:[0,1] neg_hi:[0,1]
	v_pk_add_f32 v[138:139], v[138:139], v[50:51] op_sel_hi:[1,0] neg_lo:[0,1] neg_hi:[0,1]
	v_pk_add_f32 v[122:123], v[122:123], v[50:51] op_sel_hi:[1,0] neg_lo:[0,1] neg_hi:[0,1]
	v_pk_add_f32 v[140:141], v[140:141], v[50:51] op_sel_hi:[1,0] neg_lo:[0,1] neg_hi:[0,1]
	v_pk_add_f32 v[124:125], v[124:125], v[50:51] op_sel_hi:[1,0] neg_lo:[0,1] neg_hi:[0,1]
	v_pk_add_f32 v[142:143], v[142:143], v[50:51] op_sel_hi:[1,0] neg_lo:[0,1] neg_hi:[0,1]
	v_pk_add_f32 v[126:127], v[126:127], v[50:51] op_sel_hi:[1,0] neg_lo:[0,1] neg_hi:[0,1]
	v_pk_mul_f32 v[46:47], v[46:47], v[52:53] op_sel_hi:[1,0]
	v_pk_mul_f32 v[44:45], v[44:45], v[52:53] op_sel_hi:[1,0]
	v_pk_mul_f32 v[42:43], v[42:43], v[52:53] op_sel_hi:[1,0]
	v_pk_mul_f32 v[40:41], v[40:41], v[52:53] op_sel_hi:[1,0]
	v_pk_mul_f32 v[38:39], v[38:39], v[52:53] op_sel_hi:[1,0]
	v_pk_mul_f32 v[36:37], v[36:37], v[52:53] op_sel_hi:[1,0]
	v_pk_mul_f32 v[34:35], v[34:35], v[52:53] op_sel_hi:[1,0]
	v_pk_mul_f32 v[32:33], v[32:33], v[52:53] op_sel_hi:[1,0]
	v_pk_mul_f32 v[14:15], v[14:15], v[52:53] op_sel_hi:[1,0]
	v_pk_mul_f32 v[12:13], v[12:13], v[52:53] op_sel_hi:[1,0]
	v_pk_mul_f32 v[10:11], v[10:11], v[52:53] op_sel_hi:[1,0]
	v_pk_mul_f32 v[8:9], v[8:9], v[52:53] op_sel_hi:[1,0]
	v_pk_mul_f32 v[6:7], v[6:7], v[52:53] op_sel_hi:[1,0]
	v_pk_mul_f32 v[4:5], v[4:5], v[52:53] op_sel_hi:[1,0]
	v_pk_mul_f32 v[2:3], v[2:3], v[52:53] op_sel_hi:[1,0]
	v_pk_mul_f32 v[0:1], v[0:1], v[52:53] op_sel_hi:[1,0]
	v_pk_mul_f32 v[30:31], v[30:31], v[52:53] op_sel_hi:[1,0]
	v_pk_mul_f32 v[28:29], v[28:29], v[52:53] op_sel_hi:[1,0]
	v_pk_mul_f32 v[26:27], v[26:27], v[52:53] op_sel_hi:[1,0]
	v_pk_mul_f32 v[24:25], v[24:25], v[52:53] op_sel_hi:[1,0]
	v_pk_mul_f32 v[22:23], v[22:23], v[52:53] op_sel_hi:[1,0]
	v_pk_mul_f32 v[20:21], v[20:21], v[52:53] op_sel_hi:[1,0]
	v_pk_mul_f32 v[18:19], v[18:19], v[52:53] op_sel_hi:[1,0]
	v_pk_mul_f32 v[16:17], v[16:17], v[52:53] op_sel_hi:[1,0]
	v_pk_mul_f32 v[190:191], v[190:191], v[52:53] op_sel_hi:[1,0]
	v_pk_mul_f32 v[188:189], v[188:189], v[52:53] op_sel_hi:[1,0]
	v_mov_b32_e32 v49, v48
	v_mov_b32_e32 v50, v48
	v_mov_b32_e32 v51, v48
	v_mov_b32_e32 v52, v48
	v_mov_b32_e32 v53, v48
	v_mov_b32_e32 v54, v48
	v_mov_b32_e32 v55, v48
	v_mov_b32_e32 v56, v48
	v_mov_b32_e32 v57, v48
	v_mov_b32_e32 v58, v48
	v_mov_b32_e32 v59, v48
	v_mov_b32_e32 v60, v48
	v_mov_b32_e32 v61, v48
	v_mov_b32_e32 v62, v48
	v_mov_b32_e32 v63, v48
	v_mov_b32_e32 v64, v48
	v_mov_b32_e32 v65, v48
	v_mov_b32_e32 v66, v48
	v_mov_b32_e32 v67, v48
	v_mov_b32_e32 v68, v48
	v_mov_b32_e32 v69, v48
	v_mov_b32_e32 v70, v48
	v_mov_b32_e32 v71, v48
	v_mov_b32_e32 v72, v48
	v_mov_b32_e32 v73, v48
	v_mov_b32_e32 v74, v48
	v_mov_b32_e32 v75, v48
	v_mov_b32_e32 v76, v48
	v_mov_b32_e32 v77, v48
	v_mov_b32_e32 v78, v48
	v_mov_b32_e32 v79, v48
.LBB0_530:
	s_mov_b32 m0, s79
	v_lshl_add_u64 v[80:81], v[184:185], 0, s[62:63]
	global_load_lds_dwordx4 v[80:81], off
	v_lshl_add_u64 v[80:81], v[186:187], 0, s[88:89]
	s_mov_b32 m0, s84
	s_nop 0
	global_load_lds_dwordx4 v[80:81], off
	ds_read_b128 v[80:83], v193
	ds_read_b128 v[174:177], v193 offset:4096
	s_waitcnt lgkmcnt(0)
	v_mfma_f32_32x32x16_bf16 v[96:111], v[80:83], v[152:155], v[48:63]
	ds_read_b128 v[84:87], v200
	ds_read_b128 v[180:183], v200 offset:4096
	s_setprio 1
	v_exp_f32_e32 v194, v128
	v_exp_f32_e32 v195, v129
	v_exp_f32_e32 v219, v130
	v_exp_f32_e32 v220, v131
	s_setprio 0
	s_waitcnt lgkmcnt(0)
	v_mfma_f32_32x32x16_bf16 v[96:111], v[84:87], v[144:147], v[96:111]
	ds_read_b128 v[128:131], v201
	ds_read_b128 v[184:187], v201 offset:4096
	s_setprio 1
	v_mfma_f32_32x32x16_bf16 v[80:95], v[174:177], v[152:155], v[48:63]
	v_exp_f32_e32 v132, v132
	v_exp_f32_e32 v133, v133
	v_exp_f32_e32 v134, v134
	v_exp_f32_e32 v135, v135
	s_setprio 0
	v_cvt_pk_bf16_f32 v174, v194, v195
	v_cvt_pk_bf16_f32 v175, v219, v220
	v_cvt_pk_bf16_f32 v176, v132, v133
	v_cvt_pk_bf16_f32 v177, v134, v135
	s_waitcnt lgkmcnt(0)
	v_mfma_f32_32x32x16_bf16 v[96:111], v[128:131], v[148:151], v[96:111]
	ds_read_b128 v[132:135], v202
	ds_read_b128 v[220:223], v202 offset:4096
	s_setprio 1
	v_exp_f32_e32 v128, v136
	v_exp_f32_e32 v129, v137
	v_exp_f32_e32 v130, v138
	v_exp_f32_e32 v131, v139
	s_setprio 0
	s_waitcnt lgkmcnt(0)
	v_mfma_f32_32x32x16_bf16 v[96:111], v[132:135], v[156:159], v[96:111]
	s_setprio 1
	v_mfma_f32_32x32x16_bf16 v[80:95], v[180:183], v[144:147], v[80:95]
	v_exp_f32_e32 v132, v140
	v_exp_f32_e32 v133, v141
	v_exp_f32_e32 v134, v142
	v_exp_f32_e32 v135, v143
	v_mfma_f32_32x32x16_bf16 v[80:95], v[184:187], v[148:151], v[80:95]
	s_setprio 0
	v_cvt_pk_bf16_f32 v128, v128, v129
	v_cvt_pk_bf16_f32 v129, v130, v131
	v_cvt_pk_bf16_f32 v131, v134, v135
	v_add_u32_e32 v134, 0, v209
	ds_read_b128 v[138:141], v134 offset:61440
	v_add_u32_e32 v135, s7, v209
	ds_read_b128 v[180:183], v135
	v_cvt_pk_bf16_f32 v130, v132, v133
	s_waitcnt lgkmcnt(0)
	v_mfma_f32_32x32x16_bf16 v[0:15], v[180:183], v[174:177], v[0:15]
	v_add_u32_e32 v136, 0, v211
	v_add_u32_e32 v137, s7, v211
	ds_read_b128 v[184:187], v136 offset:61440
	ds_read_b128 v[224:227], v137
	s_setprio 1
	v_mfma_f32_32x32x16_bf16 v[32:47], v[138:141], v[174:177], v[32:47]
	v_exp_f32_e32 v132, v112
	v_exp_f32_e32 v133, v115
	v_exp_f32_e32 v181, v113
	v_exp_f32_e32 v180, v114
	s_setprio 0
	s_setprio 1
	v_exp_f32_e32 v182, v116
	v_exp_f32_e32 v195, v117
	v_exp_f32_e32 v194, v118
	v_exp_f32_e32 v183, v119
	s_setprio 0
	v_cvt_pk_bf16_f32 v112, v132, v181
	v_cvt_pk_bf16_f32 v113, v180, v133
	v_cvt_pk_bf16_f32 v114, v182, v195
	v_cvt_pk_bf16_f32 v115, v194, v183
	s_waitcnt lgkmcnt(0)
	v_mfma_f32_32x32x16_bf16 v[0:15], v[224:227], v[128:131], v[0:15]
	v_add_u32_e32 v138, 0, v212
	v_add_u32_e32 v139, s7, v212
	ds_read_b128 v[116:119], v138 offset:61440
	ds_read_b128 v[140:143], v139
	s_setprio 1
	v_mfma_f32_32x32x16_bf16 v[80:95], v[220:223], v[156:159], v[80:95]
	v_exp_f32_e32 v224, v120
	v_exp_f32_e32 v227, v121
	v_exp_f32_e32 v226, v122
	v_exp_f32_e32 v225, v123
	v_add_f32_e32 v120, v180, v188
	v_add_f32_e32 v121, v181, v189
	v_add_f32_e32 v122, v132, v190
	v_add_f32_e32 v123, v133, v191
	v_add_f32_e32 v120, v194, v120
	v_add_f32_e32 v121, v195, v121
	v_mfma_f32_32x32x16_bf16 v[32:47], v[184:187], v[128:131], v[32:47]
	v_add_f32_e64 v122, v182, v122
	v_add_f32_e64 v123, v183, v123
	v_add_f32_e64 v120, v226, v120
	v_add_f32_e64 v121, v227, v121
	v_add_f32_e64 v122, v224, v122
	v_add_f32_e64 v123, v225, v123
	s_setprio 0
	s_setprio 1
	v_exp_f32_e32 v124, v124
	v_exp_f32_e32 v133, v125
	v_exp_f32_e32 v132, v126
	v_exp_f32_e32 v125, v127
	v_add_f32_e32 v188, v132, v120
	v_add_f32_e32 v189, v133, v121
	v_add_f32_e32 v190, v124, v122
	v_add_f32_e32 v191, v125, v123
	v_mov_b64_e32 v[122:123], s[38:39]
	v_mov_b64_e32 v[120:121], s[36:37]
	s_nop 1
	v_mfma_f32_32x32x16_bf16 v[16:31], v[120:123], v[174:177], v[16:31]
	v_mfma_f32_32x32x16_bf16 v[16:31], v[120:123], v[128:131], v[16:31]
	s_setprio 0
	v_cvt_pk_bf16_f32 v120, v224, v227
	v_cvt_pk_bf16_f32 v121, v226, v225
	v_cvt_pk_bf16_f32 v122, v124, v133
	v_cvt_pk_bf16_f32 v123, v132, v125
	s_waitcnt lgkmcnt(0)
	v_mfma_f32_32x32x16_bf16 v[32:47], v[116:119], v[112:115], v[32:47]
	v_add_u32_e32 v132, 0, v214
	v_add_u32_e32 v133, s7, v214
	ds_read_b128 v[124:127], v132 offset:61440
	ds_read_b128 v[128:131], v133
	v_mfma_f32_32x32x16_bf16 v[0:15], v[140:143], v[112:115], v[0:15]
	v_max_f32_e32 v112, v96, v96
	v_max_f32_e32 v112, 0xf149f2ca, v112
	v_max3_f32 v113, v98, s72, v99
	v_max3_f32 v112, v112, v97, v100
	v_max3_f32 v113, v113, v102, v103
	v_max3_f32 v112, v112, v101, v104
	v_max3_f32 v113, v113, v106, v107
	v_max3_f32 v112, v112, v105, v108
	v_max3_f32 v113, v113, v110, v111
	s_waitcnt lgkmcnt(0)
	v_mfma_f32_32x32x16_bf16 v[32:47], v[124:127], v[120:123], v[32:47]
	v_max3_f32 v112, v112, v109, v80
	v_max3_f32 v113, v113, v82, v83
	v_max3_f32 v112, v112, v81, v84
	v_max3_f32 v113, v113, v86, v87
	v_max3_f32 v112, v112, v85, v88
	v_max3_f32 v113, v113, v90, v91
	v_max3_f32 v112, v112, v89, v92
	v_mfma_f32_32x32x16_bf16 v[0:15], v[128:131], v[120:123], v[0:15]
	v_max3_f32 v113, v113, v94, v95
	v_max3_f32 v112, v112, v93, v113
	v_mov_b32_e32 v113, v112
	s_nop 1
	v_permlane32_swap_b32_e32 v112, v113
	s_waitcnt vmcnt(2)
	v_max_f32_e32 v113, v113, v113
	v_max_f32_e32 v112, v112, v112
	s_waitcnt lgkmcnt(0)
	s_barrier
	v_max_f32_e32 v112, v112, v113
	v_cmp_lt_f32_e32 vcc, s96, v112
	s_cbranch_vccz .LBB0_522
	v_max_f32_e32 v48, v112, v112
	v_max_f32_e32 v49, 0, v48
	v_exp_f32_e64 v50, -v49
	v_add_f32_e32 v206, v206, v49
	v_xor_b32_e32 v48, 0x80000000, v206
	v_sub_f32_e32 v111, v111, v49
	v_sub_f32_e32 v110, v110, v49
	v_sub_f32_e32 v109, v109, v49
	v_sub_f32_e32 v108, v108, v49
	v_sub_f32_e32 v107, v107, v49
	v_sub_f32_e32 v106, v106, v49
	v_sub_f32_e32 v105, v105, v49
	v_sub_f32_e32 v104, v104, v49
	v_sub_f32_e32 v103, v103, v49
	v_sub_f32_e32 v102, v102, v49
	v_sub_f32_e32 v101, v101, v49
	v_sub_f32_e32 v100, v100, v49
	v_sub_f32_e32 v99, v99, v49
	v_sub_f32_e32 v98, v98, v49
	v_sub_f32_e32 v97, v97, v49
	v_sub_f32_e32 v96, v96, v49
	v_sub_f32_e32 v95, v95, v49
	v_sub_f32_e32 v94, v94, v49
	v_sub_f32_e32 v93, v93, v49
	v_sub_f32_e32 v92, v92, v49
	v_sub_f32_e32 v91, v91, v49
	v_sub_f32_e32 v90, v90, v49
	v_sub_f32_e32 v89, v89, v49
	v_sub_f32_e32 v88, v88, v49
	v_sub_f32_e32 v87, v87, v49
	v_sub_f32_e32 v86, v86, v49
	v_sub_f32_e32 v85, v85, v49
	v_sub_f32_e32 v84, v84, v49
	v_sub_f32_e32 v83, v83, v49
	v_sub_f32_e32 v82, v82, v49
	v_sub_f32_e32 v81, v81, v49
	v_sub_f32_e32 v80, v80, v49
	v_pk_mul_f32 v[46:47], v[46:47], v[50:51] op_sel_hi:[1,0]
	v_pk_mul_f32 v[44:45], v[44:45], v[50:51] op_sel_hi:[1,0]
	v_pk_mul_f32 v[42:43], v[42:43], v[50:51] op_sel_hi:[1,0]
	v_pk_mul_f32 v[40:41], v[40:41], v[50:51] op_sel_hi:[1,0]
	v_pk_mul_f32 v[38:39], v[38:39], v[50:51] op_sel_hi:[1,0]
	v_pk_mul_f32 v[36:37], v[36:37], v[50:51] op_sel_hi:[1,0]
	v_pk_mul_f32 v[34:35], v[34:35], v[50:51] op_sel_hi:[1,0]
	v_pk_mul_f32 v[32:33], v[32:33], v[50:51] op_sel_hi:[1,0]
	v_pk_mul_f32 v[14:15], v[14:15], v[50:51] op_sel_hi:[1,0]
	v_pk_mul_f32 v[12:13], v[12:13], v[50:51] op_sel_hi:[1,0]
	v_pk_mul_f32 v[10:11], v[10:11], v[50:51] op_sel_hi:[1,0]
	v_pk_mul_f32 v[8:9], v[8:9], v[50:51] op_sel_hi:[1,0]
	v_pk_mul_f32 v[6:7], v[6:7], v[50:51] op_sel_hi:[1,0]
	v_pk_mul_f32 v[4:5], v[4:5], v[50:51] op_sel_hi:[1,0]
	v_pk_mul_f32 v[2:3], v[2:3], v[50:51] op_sel_hi:[1,0]
	v_pk_mul_f32 v[0:1], v[0:1], v[50:51] op_sel_hi:[1,0]
	v_pk_mul_f32 v[30:31], v[30:31], v[50:51] op_sel_hi:[1,0]
	v_pk_mul_f32 v[28:29], v[28:29], v[50:51] op_sel_hi:[1,0]
	v_pk_mul_f32 v[26:27], v[26:27], v[50:51] op_sel_hi:[1,0]
	v_pk_mul_f32 v[24:25], v[24:25], v[50:51] op_sel_hi:[1,0]
	v_pk_mul_f32 v[22:23], v[22:23], v[50:51] op_sel_hi:[1,0]
	v_pk_mul_f32 v[20:21], v[20:21], v[50:51] op_sel_hi:[1,0]
	v_pk_mul_f32 v[18:19], v[18:19], v[50:51] op_sel_hi:[1,0]
	v_pk_mul_f32 v[16:17], v[16:17], v[50:51] op_sel_hi:[1,0]
	v_pk_mul_f32 v[190:191], v[190:191], v[50:51] op_sel_hi:[1,0]
	v_pk_mul_f32 v[188:189], v[188:189], v[50:51] op_sel_hi:[1,0]
	v_mov_b32_e32 v49, v48
	v_mov_b32_e32 v50, v48
	v_mov_b32_e32 v51, v48
	v_mov_b32_e32 v52, v48
	v_mov_b32_e32 v53, v48
	v_mov_b32_e32 v54, v48
	v_mov_b32_e32 v55, v48
	v_mov_b32_e32 v56, v48
	v_mov_b32_e32 v57, v48
	v_mov_b32_e32 v58, v48
	v_mov_b32_e32 v59, v48
	v_mov_b32_e32 v60, v48
	v_mov_b32_e32 v61, v48
	v_mov_b32_e32 v62, v48
	v_mov_b32_e32 v63, v48
	v_mov_b32_e32 v64, v48
	v_mov_b32_e32 v65, v48
	v_mov_b32_e32 v66, v48
	v_mov_b32_e32 v67, v48
	v_mov_b32_e32 v68, v48
	v_mov_b32_e32 v69, v48
	v_mov_b32_e32 v70, v48
	v_mov_b32_e32 v71, v48
	v_mov_b32_e32 v72, v48
	v_mov_b32_e32 v73, v48
	v_mov_b32_e32 v74, v48
	v_mov_b32_e32 v75, v48
	v_mov_b32_e32 v76, v48
	v_mov_b32_e32 v77, v48
	v_mov_b32_e32 v78, v48
	v_mov_b32_e32 v79, v48
	s_branch .LBB0_522

; #define DMA_WAIT(keep) do { if (keep) { if (TYPE == 0 && wid < 4) asm volatile("s_waitcnt vmcnt(3)" ::: "memory"); else asm volatile("s_waitcnt vmcnt(2)" ::: "memory"); } \
;     else asm volatile("s_waitcnt vmcnt(0)" ::: "memory"); } while (0)
; #define BAR() do { asm volatile("s_waitcnt lgkmcnt(0)" ::: "memory"); __builtin_amdgcn_s_barrier(); asm volatile("" ::: "memory"); } while (0)
; #define QKR(d0, K0, K1, SOFF) do { if ((d0) < 4) { K0 = *(const bf16x8*)(lds + (SOFF) + koff[(d0) & 3]); K1 = *(const bf16x8*)(lds + (SOFF) + 32 * 128 + koff[(d0) & 3]); } \
;     else if ((d0) < NQK) { K0 = *(const bf16x8*)(lds + (SOFF) + roff[(d0) & 1]); K1 = *(const bf16x8*)(lds + (SOFF) + 32 * 64 + roff[(d0) & 1]); } } while (0)
; #define QKM(N0, N1, d0, K0, K1) do { if ((d0) == 0) { N0 = MFMA(K0, qf[0], negm); N1 = MFMA(K1, qf[0], negm); } \
;     else if ((d0) < NQK) { N0 = MFMA(K0, qf[(d0) < NQK ? (d0) : 0], N0); N1 = MFMA(K1, qf[(d0) < NQK ? (d0) : 0], N1); } } while (0)
; template <int TYPE, bool FIXREF>
; DI void attn_dense_unit(const Params& p, int layer, int head, int qb, char* lds, float bref) {
;     ...
;   constexpr int R0 = 0, R1 = ATT_STAGE, R2 = 2 * ATT_STAGE, R3 = 3 * ATT_STAGE;
;   f32x16 sA0, sA1, sB0, sB1;
;   DMA(0, R0); DMA(1, R1); DMA(2, R2); DMA_WAIT(true); BAR();
;   if (FIXREF) { m_run = bref;
; #pragma unroll
;     for (int i = 0; i < 16; ++i) negm[i] = -bref; }
;   { bf16x8 ka0, ka1;
; #pragma unroll
;     for (int d0 = 0; d0 < NQK; ++d0) { QKR(d0, ka0, ka1, R0); QKM(sA0, sA1, d0, ka0, ka1); } }
;   if (!FIXREF) { float mx0; ROWMAX(sA0, sA1, mx0); m_run = mx0;
; #pragma unroll
;     for (int i = 0; i < 16; ++i) { sA0[i] -= mx0; sA1[i] -= mx0; negm[i] = -mx0; } }
;   for (int t = 0; t < NT - 4; t += 4) {
;     STEP(sA0, sA1, sB0, sB1, t, true, true, R0, R1, R3);
;     STEP(sB0, sB1, sA0, sA1, t + 1, true, true, R1, R2, R0);
;     STEP(sA0, sA1, sB0, sB1, t + 2, true, true, R2, R3, R1);
;     STEP(sB0, sB1, sA0, sA1, t + 3, true, true, R3, R0, R2);
;   }
.LBB0_541:
	v_lshl_add_u64 v[164:165], v[160:161], 0, v[172:173]
	s_add_i32 s10, s0, 0xf000
	v_lshl_add_u64 v[96:97], v[164:165], 0, s[12:13]
	s_mov_b32 m0, s10
	v_lshl_add_u64 v[166:167], v[158:159], 0, v[172:173]
	global_load_lds_dwordx4 v[96:97], off
	v_lshl_add_u64 v[96:97], v[166:167], 0, s[14:15]
	s_mov_b32 m0, s8
	s_nop 0
	global_load_lds_dwordx4 v[96:97], off
	ds_read_b128 v[96:99], v201 offset:20480
	ds_read_b128 v[144:147], v201 offset:24576
	ds_read_b128 v[100:103], v202 offset:20480
	ds_read_b128 v[168:171], v202 offset:24576
	v_exp_f32_e32 v180, v80
	v_exp_f32_e32 v181, v81
	v_exp_f32_e32 v182, v82
	v_exp_f32_e32 v183, v83
	s_waitcnt lgkmcnt(0)
	v_mfma_f32_32x32x16_bf16 v[112:127], v[96:99], v[132:135], v[48:63]
	ds_read_b128 v[80:83], v204 offset:20480
	ds_read_b128 v[174:177], v204 offset:24576
	v_exp_f32_e32 v84, v84
	v_exp_f32_e32 v85, v85
	v_exp_f32_e32 v86, v86
	v_exp_f32_e32 v87, v87
	v_mfma_f32_32x32x16_bf16 v[112:127], v[100:103], v[128:131], v[112:127]
	v_cvt_pk_bf16_f32 v180, v180, v181
	v_cvt_pk_bf16_f32 v181, v182, v183
	v_cvt_pk_bf16_f32 v182, v84, v85
	v_cvt_pk_bf16_f32 v183, v86, v87
	v_mfma_f32_32x32x16_bf16 v[96:111], v[144:147], v[132:135], v[48:63]
	ds_read_b128 v[84:87], v203 offset:20480
	ds_read_b128 v[144:147], v203 offset:24576
	s_waitcnt lgkmcnt(0)
	v_mfma_f32_32x32x16_bf16 v[112:127], v[80:83], v[140:143], v[112:127]
	v_exp_f32_e32 v80, v88
	v_exp_f32_e32 v81, v89
	v_exp_f32_e32 v82, v90
	v_exp_f32_e32 v83, v91
	v_mfma_f32_32x32x16_bf16 v[112:127], v[84:87], v[136:139], v[112:127]
	v_exp_f32_e32 v84, v92
	v_exp_f32_e32 v85, v93
	v_exp_f32_e32 v86, v94
	v_exp_f32_e32 v87, v95
	v_mfma_f32_32x32x16_bf16 v[96:111], v[168:171], v[128:131], v[96:111]
	v_cvt_pk_bf16_f32 v168, v80, v81
	v_cvt_pk_bf16_f32 v169, v82, v83
	v_cvt_pk_bf16_f32 v170, v84, v85
	v_cvt_pk_bf16_f32 v171, v86, v87
	ds_read_b128 v[80:83], v206 offset:8192
	ds_read_b128 v[84:87], v206 offset:12288
	v_mfma_f32_32x32x16_bf16 v[96:111], v[174:177], v[140:143], v[96:111]
	s_waitcnt lgkmcnt(0)
	v_mfma_f32_32x32x16_bf16 v[0:15], v[84:87], v[180:183], v[0:15]
	ds_read_b128 v[88:91], v205 offset:8192
	ds_read_b128 v[92:95], v205 offset:12288
	v_exp_f32_e32 v217, v64
	v_exp_f32_e32 v218, v65
	v_exp_f32_e32 v219, v66
	v_exp_f32_e32 v216, v67
	v_exp_f32_e32 v221, v68
	v_exp_f32_e32 v222, v69
	v_mfma_f32_32x32x16_bf16 v[16:31], v[80:83], v[180:183], v[16:31]
	v_exp_f32_e32 v223, v70
	v_exp_f32_e32 v220, v71
	v_cvt_pk_bf16_f32 v64, v217, v218
	v_cvt_pk_bf16_f32 v65, v219, v216
	v_cvt_pk_bf16_f32 v66, v221, v222
	v_cvt_pk_bf16_f32 v67, v223, v220
	s_waitcnt lgkmcnt(0)
	v_mfma_f32_32x32x16_bf16 v[0:15], v[92:95], v[168:171], v[0:15]
	ds_read_b128 v[68:71], v200 offset:8192
	ds_read_b128 v[174:177], v200 offset:12288
	v_exp_f32_e32 v225, v72
	v_exp_f32_e32 v226, v73
	v_exp_f32_e32 v227, v74
	v_exp_f32_e32 v224, v75
	v_exp_f32_e32 v229, v76
	v_exp_f32_e32 v230, v77
	v_mfma_f32_32x32x16_bf16 v[16:31], v[88:91], v[168:171], v[16:31]
	v_exp_f32_e32 v231, v78
	v_exp_f32_e32 v228, v79
	v_cvt_pk_bf16_f32 v72, v225, v226
	v_cvt_pk_bf16_f32 v73, v227, v224
	v_cvt_pk_bf16_f32 v74, v229, v230
	v_cvt_pk_bf16_f32 v75, v231, v228
	v_mfma_f32_32x32x16_bf16 v[96:111], v[144:147], v[136:139], v[96:111]
	s_waitcnt lgkmcnt(0)
	v_mfma_f32_32x32x16_bf16 v[16:31], v[68:71], v[64:67], v[16:31]
	ds_read_b128 v[76:79], v151 offset:8192
	ds_read_b128 v[184:187], v151 offset:12288
	s_waitcnt lgkmcnt(0)
	v_mfma_f32_32x32x16_bf16 v[16:31], v[76:79], v[72:75], v[16:31]
	s_waitcnt vmcnt(2)
	s_mov_b32 m0, s0
	s_waitcnt lgkmcnt(0)
	s_barrier
	v_lshl_add_u64 v[68:69], v[164:165], 0, s[16:17]
	global_load_lds_dwordx4 v[68:69], off
	v_lshl_add_u64 v[68:69], v[166:167], 0, s[18:19]
	s_mov_b32 m0, s1
	s_nop 0
	global_load_lds_dwordx4 v[68:69], off
	ds_read_b128 v[68:71], v201 offset:40960
	ds_read_b128 v[188:191], v201 offset:45056
	v_mfma_f32_32x32x16_bf16 v[0:15], v[174:177], v[64:67], v[0:15]
	v_mov_b64_e32 v[146:147], s[38:39]
	v_mov_b64_e32 v[144:145], s[36:37]
	ds_read_b128 v[64:67], v202 offset:40960
	ds_read_b128 v[174:177], v202 offset:45056
	v_exp_f32_e32 v192, v112
	v_exp_f32_e32 v193, v113
	v_exp_f32_e32 v194, v114
	v_exp_f32_e32 v195, v115
	s_waitcnt lgkmcnt(0)
	v_mfma_f32_32x32x16_bf16 v[80:95], v[68:71], v[132:135], v[48:63]
	v_mfma_f32_32x32x16_bf16 v[32:47], v[144:147], v[180:183], v[32:47]
	v_mfma_f32_32x32x16_bf16 v[0:15], v[184:187], v[72:75], v[0:15]
	v_mfma_f32_32x32x16_bf16 v[80:95], v[64:67], v[128:131], v[80:95]
	ds_read_b128 v[112:115], v204 offset:40960
	ds_read_b128 v[180:183], v204 offset:45056
	v_exp_f32_e32 v116, v116
	v_exp_f32_e32 v117, v117
	v_exp_f32_e32 v118, v118
	v_exp_f32_e32 v119, v119
	v_cvt_pk_bf16_f32 v192, v192, v193
	v_cvt_pk_bf16_f32 v193, v194, v195
	v_mfma_f32_32x32x16_bf16 v[64:79], v[188:191], v[132:135], v[48:63]
	v_cvt_pk_bf16_f32 v194, v116, v117
	v_cvt_pk_bf16_f32 v195, v118, v119
	s_waitcnt lgkmcnt(0)
	v_mfma_f32_32x32x16_bf16 v[80:95], v[112:115], v[140:143], v[80:95]
	ds_read_b128 v[112:115], v203 offset:40960
	ds_read_b128 v[116:119], v203 offset:45056
	v_exp_f32_e32 v120, v120
	v_exp_f32_e32 v121, v121
	v_exp_f32_e32 v122, v122
	v_exp_f32_e32 v123, v123
	v_mfma_f32_32x32x16_bf16 v[32:47], v[144:147], v[168:171], v[32:47]
	v_mfma_f32_32x32x16_bf16 v[64:79], v[174:177], v[128:131], v[64:79]
	v_cvt_pk_bf16_f32 v174, v120, v121
	v_cvt_pk_bf16_f32 v175, v122, v123
	s_waitcnt lgkmcnt(0)
	v_mfma_f32_32x32x16_bf16 v[80:95], v[112:115], v[136:139], v[80:95]
	v_exp_f32_e32 v112, v124
	v_exp_f32_e32 v113, v125
	v_exp_f32_e32 v114, v126
	v_exp_f32_e32 v115, v127
	v_cvt_pk_bf16_f32 v176, v112, v113
	v_cvt_pk_bf16_f32 v177, v114, v115
	v_mfma_f32_32x32x16_bf16 v[64:79], v[180:183], v[140:143], v[64:79]
	ds_read_b128 v[112:115], v206 offset:28672
	ds_read_b128 v[120:123], v206 offset:32768
	s_waitcnt lgkmcnt(0)
	v_mfma_f32_32x32x16_bf16 v[0:15], v[120:123], v[192:195], v[0:15]
	ds_read_b128 v[124:127], v205 offset:28672
	ds_read_b128 v[180:183], v205 offset:32768
	v_exp_f32_e32 v121, v96
	v_exp_f32_e32 v96, v97
	v_exp_f32_e32 v97, v98
	v_add_f32_e32 v122, v162, v218
	v_add_f32_e32 v123, v163, v219
	v_exp_f32_e32 v120, v99
	v_add_f32_e32 v98, v156, v216
	v_add_f32_e32 v99, v157, v217
	v_mfma_f32_32x32x16_bf16 v[16:31], v[112:115], v[192:195], v[16:31]
	v_add_f32_e64 v122, v222, v122
	v_add_f32_e64 v123, v223, v123
	v_add_f32_e64 v98, v220, v98
	v_add_f32_e64 v99, v221, v99
	v_exp_f32_e32 v163, v100
	v_exp_f32_e32 v184, v101
	v_exp_f32_e32 v185, v102
	v_exp_f32_e32 v162, v103
	v_add_f32_e32 v122, v226, v122
	v_add_f32_e32 v123, v227, v123
	v_add_f32_e32 v98, v224, v98
	v_add_f32_e32 v99, v225, v99
	v_add_f32_e32 v122, v230, v122
	v_add_f32_e32 v123, v231, v123
	v_add_f32_e32 v98, v228, v98
	v_add_f32_e32 v99, v229, v99
	v_add_f32_e32 v168, v122, v96
	v_add_f32_e32 v169, v123, v97
	v_add_f32_e32 v156, v98, v120
	v_add_f32_e32 v157, v99, v121
	v_cvt_pk_bf16_f32 v96, v121, v96
	v_cvt_pk_bf16_f32 v97, v97, v120
	v_cvt_pk_bf16_f32 v98, v163, v184
	v_cvt_pk_bf16_f32 v99, v185, v162
	s_waitcnt lgkmcnt(0)
	v_mfma_f32_32x32x16_bf16 v[0:15], v[180:183], v[174:177], v[0:15]
	ds_read_b128 v[100:103], v200 offset:28672
	ds_read_b128 v[180:183], v200 offset:32768
	v_exp_f32_e32 v171, v104
	v_exp_f32_e32 v188, v105
	v_exp_f32_e32 v189, v106
	v_exp_f32_e32 v170, v107
	v_exp_f32_e32 v187, v108
	v_exp_f32_e32 v190, v109
	v_mfma_f32_32x32x16_bf16 v[64:79], v[116:119], v[136:139], v[64:79]
	v_exp_f32_e32 v191, v110
	v_exp_f32_e32 v186, v111
	v_cvt_pk_bf16_f32 v104, v171, v188
	v_cvt_pk_bf16_f32 v105, v189, v170
	v_cvt_pk_bf16_f32 v106, v187, v190
	v_cvt_pk_bf16_f32 v107, v191, v186
	v_mfma_f32_32x32x16_bf16 v[16:31], v[124:127], v[174:177], v[16:31]
	s_waitcnt lgkmcnt(0)
	v_mfma_f32_32x32x16_bf16 v[16:31], v[100:103], v[96:99], v[16:31]
	ds_read_b128 v[108:111], v151 offset:28672
	ds_read_b128 v[218:221], v151 offset:32768
	s_waitcnt lgkmcnt(0)
	v_mfma_f32_32x32x16_bf16 v[16:31], v[108:111], v[104:107], v[16:31]
	s_waitcnt vmcnt(2)
	s_mov_b32 m0, s4
	s_waitcnt lgkmcnt(0)
	s_barrier
	v_lshl_add_u64 v[100:101], v[164:165], 0, s[34:35]
	global_load_lds_dwordx4 v[100:101], off
	v_lshl_add_u64 v[100:101], v[166:167], 0, s[42:43]
	s_mov_b32 m0, s5
	s_add_i32 s11, 0, 0x10000
	global_load_lds_dwordx4 v[100:101], off
	v_add_u32_e32 v215, s11, v207
	ds_read_b128 v[100:103], v201 offset:61440
	ds_read_b128 v[222:225], v215
	v_mfma_f32_32x32x16_bf16 v[0:15], v[180:183], v[96:99], v[0:15]
	v_add_u32_e32 v216, s11, v208
	ds_read_b128 v[96:99], v202 offset:61440
	ds_read_b128 v[180:183], v216
	v_exp_f32_e32 v226, v80
	v_exp_f32_e32 v227, v81
	v_exp_f32_e32 v228, v82
	v_exp_f32_e32 v229, v83
	v_mfma_f32_32x32x16_bf16 v[32:47], v[144:147], v[192:195], v[32:47]
	v_mfma_f32_32x32x16_bf16 v[0:15], v[218:221], v[104:107], v[0:15]
	s_waitcnt lgkmcnt(0)
	v_mfma_f32_32x32x16_bf16 v[112:127], v[100:103], v[132:135], v[48:63]
	ds_read_b128 v[80:83], v204 offset:61440
	v_add_u32_e32 v217, s11, v209
	ds_read_b128 v[192:195], v217
	v_exp_f32_e32 v84, v84
	v_exp_f32_e32 v85, v85
	v_exp_f32_e32 v86, v86
	v_exp_f32_e32 v87, v87
	v_cvt_pk_bf16_f32 v220, v226, v227
	v_mfma_f32_32x32x16_bf16 v[112:127], v[96:99], v[128:131], v[112:127]
	v_cvt_pk_bf16_f32 v221, v228, v229
	v_mfma_f32_32x32x16_bf16 v[96:111], v[222:225], v[132:135], v[48:63]
	v_cvt_pk_bf16_f32 v222, v84, v85
	v_cvt_pk_bf16_f32 v223, v86, v87
	v_mfma_f32_32x32x16_bf16 v[32:47], v[144:147], v[174:177], v[32:47]
	v_add_u32_e32 v218, s11, v210
	v_exp_f32_e32 v88, v88
	v_exp_f32_e32 v89, v89
	v_exp_f32_e32 v90, v90
	v_exp_f32_e32 v91, v91
	s_waitcnt lgkmcnt(0)
	v_mfma_f32_32x32x16_bf16 v[112:127], v[80:83], v[140:143], v[112:127]
	ds_read_b128 v[80:83], v203 offset:61440
	ds_read_b128 v[84:87], v218
	s_waitcnt lgkmcnt(0)
	v_mfma_f32_32x32x16_bf16 v[112:127], v[80:83], v[136:139], v[112:127]
	v_exp_f32_e32 v80, v92
	v_exp_f32_e32 v81, v93
	v_exp_f32_e32 v82, v94
	v_exp_f32_e32 v83, v95
	v_cvt_pk_bf16_f32 v174, v88, v89
	v_cvt_pk_bf16_f32 v175, v90, v91
	v_cvt_pk_bf16_f32 v176, v80, v81
	v_mfma_f32_32x32x16_bf16 v[96:111], v[180:183], v[128:131], v[96:111]
	v_cvt_pk_bf16_f32 v177, v82, v83
	ds_read_b128 v[80:83], v206 offset:49152
	ds_read_b128 v[88:91], v206 offset:53248
	v_mfma_f32_32x32x16_bf16 v[96:111], v[192:195], v[140:143], v[96:111]
	s_waitcnt lgkmcnt(0)
	v_mfma_f32_32x32x16_bf16 v[0:15], v[88:91], v[220:223], v[0:15]
	ds_read_b128 v[92:95], v205 offset:49152
	ds_read_b128 v[180:183], v205 offset:53248
	v_exp_f32_e32 v193, v64
	v_exp_f32_e32 v194, v65
	v_exp_f32_e32 v195, v66
	v_exp_f32_e32 v192, v67
	v_exp_f32_e32 v229, v68
	v_exp_f32_e32 v230, v69
	v_mfma_f32_32x32x16_bf16 v[16:31], v[80:83], v[220:223], v[16:31]
	v_exp_f32_e32 v231, v70
	v_exp_f32_e32 v228, v71
	v_cvt_pk_bf16_f32 v64, v193, v194
	v_cvt_pk_bf16_f32 v65, v195, v192
	v_cvt_pk_bf16_f32 v66, v229, v230
	v_cvt_pk_bf16_f32 v67, v231, v228
	s_waitcnt lgkmcnt(0)
	v_mfma_f32_32x32x16_bf16 v[0:15], v[180:183], v[174:177], v[0:15]
	ds_read_b128 v[68:71], v200 offset:49152
	ds_read_b128 v[180:183], v200 offset:53248
	v_exp_f32_e32 v233, v72
	v_exp_f32_e32 v234, v73
	v_exp_f32_e32 v235, v74
	v_exp_f32_e32 v232, v75
	v_exp_f32_e32 v237, v76
	v_exp_f32_e32 v238, v77
	v_mfma_f32_32x32x16_bf16 v[16:31], v[92:95], v[174:177], v[16:31]
	v_exp_f32_e32 v239, v78
	v_exp_f32_e32 v236, v79
	v_cvt_pk_bf16_f32 v72, v233, v234
	v_cvt_pk_bf16_f32 v73, v235, v232
	v_cvt_pk_bf16_f32 v74, v237, v238
	v_cvt_pk_bf16_f32 v75, v239, v236
	v_mfma_f32_32x32x16_bf16 v[96:111], v[84:87], v[136:139], v[96:111]
	s_waitcnt lgkmcnt(0)
	v_mfma_f32_32x32x16_bf16 v[16:31], v[68:71], v[64:67], v[16:31]
	ds_read_b128 v[76:79], v151 offset:49152
	ds_read_b128 v[224:227], v151 offset:53248
	s_waitcnt lgkmcnt(0)
	v_mfma_f32_32x32x16_bf16 v[16:31], v[76:79], v[72:75], v[16:31]
	s_waitcnt vmcnt(2)
	s_mov_b32 m0, s6
	s_waitcnt lgkmcnt(0)
	s_barrier
; #define DMA_WAIT(keep) do { if (keep) { if (TYPE == 0 && wid < 4) asm volatile("s_waitcnt vmcnt(3)" ::: "memory"); else asm volatile("s_waitcnt vmcnt(2)" ::: "memory"); } \
;     else asm volatile("s_waitcnt vmcnt(0)" ::: "memory"); } while (0)
; #define BAR() do { asm volatile("s_waitcnt lgkmcnt(0)" ::: "memory"); __builtin_amdgcn_s_barrier(); asm volatile("" ::: "memory"); } while (0)
; #define QKR(d0, K0, K1, SOFF) do { if ((d0) < 4) { K0 = *(const bf16x8*)(lds + (SOFF) + koff[(d0) & 3]); K1 = *(const bf16x8*)(lds + (SOFF) + 32 * 128 + koff[(d0) & 3]); } \
;     else if ((d0) < NQK) { K0 = *(const bf16x8*)(lds + (SOFF) + roff[(d0) & 1]); K1 = *(const bf16x8*)(lds + (SOFF) + 32 * 64 + roff[(d0) & 1]); } } while (0)
; #define QKM(N0, N1, d0, K0, K1) do { if ((d0) == 0) { N0 = MFMA(K0, qf[0], negm); N1 = MFMA(K1, qf[0], negm); } \
;     else if ((d0) < NQK) { N0 = MFMA(K0, qf[(d0) < NQK ? (d0) : 0], N0); N1 = MFMA(K1, qf[(d0) < NQK ? (d0) : 0], N1); } } while (0)
; template <int TYPE, bool FIXREF>
; DI void attn_dense_unit(const Params& p, int layer, int head, int qb, char* lds, float bref) {
;     ...
;   constexpr int R0 = 0, R1 = ATT_STAGE, R2 = 2 * ATT_STAGE, R3 = 3 * ATT_STAGE;
;   f32x16 sA0, sA1, sB0, sB1;
;   DMA(0, R0); DMA(1, R1); DMA(2, R2); DMA_WAIT(true); BAR();
;   if (FIXREF) { m_run = bref;
; #pragma unroll
;     for (int i = 0; i < 16; ++i) negm[i] = -bref; }
;   { bf16x8 ka0, ka1;
; #pragma unroll
;     for (int d0 = 0; d0 < NQK; ++d0) { QKR(d0, ka0, ka1, R0); QKM(sA0, sA1, d0, ka0, ka1); } }
;   if (!FIXREF) { float mx0; ROWMAX(sA0, sA1, mx0); m_run = mx0;
; #pragma unroll
;     for (int i = 0; i < 16; ++i) { sA0[i] -= mx0; sA1[i] -= mx0; negm[i] = -mx0; } }
;   for (int t = 0; t < NT - 4; t += 4) {
;     STEP(sA0, sA1, sB0, sB1, t, true, true, R0, R1, R3);
;     STEP(sB0, sB1, sA0, sA1, t + 1, true, true, R1, R2, R0);
;     STEP(sA0, sA1, sB0, sB1, t + 2, true, true, R2, R3, R1);
;     STEP(sB0, sB1, sA0, sA1, t + 3, true, true, R3, R0, R2);
;   }
	v_lshl_add_u64 v[68:69], v[164:165], 0, s[44:45]
	global_load_lds_dwordx4 v[68:69], off
	v_lshl_add_u64 v[68:69], v[166:167], 0, s[46:47]
	s_mov_b32 m0, s7
	s_nop 0
	global_load_lds_dwordx4 v[68:69], off
	ds_read_b128 v[68:71], v201
	ds_read_b128 v[164:167], v201 offset:4096
	v_mfma_f32_32x32x16_bf16 v[0:15], v[180:183], v[64:67], v[0:15]
	ds_read_b128 v[64:67], v202
	ds_read_b128 v[180:183], v202 offset:4096
	s_waitcnt lgkmcnt(0)
	v_mfma_f32_32x32x16_bf16 v[80:95], v[68:71], v[132:135], v[48:63]
	v_exp_f32_e32 v68, v112
	v_exp_f32_e32 v69, v113
	v_exp_f32_e32 v70, v114
	v_exp_f32_e32 v71, v115
	v_mfma_f32_32x32x16_bf16 v[32:47], v[144:147], v[220:223], v[32:47]
	v_mfma_f32_32x32x16_bf16 v[0:15], v[224:227], v[72:75], v[0:15]
	v_mfma_f32_32x32x16_bf16 v[80:95], v[64:67], v[128:131], v[80:95]
	v_exp_f32_e32 v64, v116
	v_exp_f32_e32 v65, v117
	v_exp_f32_e32 v66, v118
	v_exp_f32_e32 v67, v119
	v_cvt_pk_bf16_f32 v116, v68, v69
	v_cvt_pk_bf16_f32 v117, v70, v71
	v_cvt_pk_bf16_f32 v118, v64, v65
	v_cvt_pk_bf16_f32 v119, v66, v67
	v_mfma_f32_32x32x16_bf16 v[64:79], v[164:167], v[132:135], v[48:63]
	ds_read_b128 v[112:115], v204
	ds_read_b128 v[220:223], v204 offset:4096
	s_waitcnt lgkmcnt(0)
	v_mfma_f32_32x32x16_bf16 v[80:95], v[112:115], v[140:143], v[80:95]
	ds_read_b128 v[112:115], v203
	ds_read_b128 v[224:227], v203 offset:4096
	v_exp_f32_e32 v120, v120
	v_exp_f32_e32 v121, v121
	v_exp_f32_e32 v122, v122
	v_exp_f32_e32 v123, v123
	v_mfma_f32_32x32x16_bf16 v[32:47], v[144:147], v[174:177], v[32:47]
	v_mfma_f32_32x32x16_bf16 v[64:79], v[180:183], v[128:131], v[64:79]
	v_add_u32_e32 v166, 0, v211
	v_add_u32_e32 v167, s11, v211
	s_waitcnt lgkmcnt(0)
	v_mfma_f32_32x32x16_bf16 v[80:95], v[112:115], v[136:139], v[80:95]
	v_exp_f32_e32 v114, v124
	v_exp_f32_e32 v115, v125
	v_exp_f32_e32 v124, v126
	v_exp_f32_e32 v125, v127
	v_cvt_pk_bf16_f32 v112, v120, v121
	v_cvt_pk_bf16_f32 v113, v122, v123
	v_cvt_pk_bf16_f32 v114, v114, v115
	v_mfma_f32_32x32x16_bf16 v[64:79], v[220:223], v[140:143], v[64:79]
	v_cvt_pk_bf16_f32 v115, v124, v125
	ds_read_b128 v[120:123], v166 offset:61440
	ds_read_b128 v[124:127], v167
	s_waitcnt lgkmcnt(0)
	v_mfma_f32_32x32x16_bf16 v[0:15], v[124:127], v[116:119], v[0:15]
	v_add_u32_e32 v164, 0, v212
	v_add_u32_e32 v165, s11, v212
	ds_read_b128 v[174:177], v164 offset:61440
	ds_read_b128 v[180:183], v165
	v_exp_f32_e32 v127, v96
	v_exp_f32_e32 v222, v97
	v_exp_f32_e32 v223, v98
	v_mfma_f32_32x32x16_bf16 v[16:31], v[120:123], v[116:119], v[16:31]
	v_exp_f32_e32 v126, v99
	v_exp_f32_e32 v241, v100
	v_exp_f32_e32 v242, v101
	v_exp_f32_e32 v243, v102
	v_exp_f32_e32 v240, v103
	v_cvt_pk_bf16_f32 v96, v127, v222
	v_cvt_pk_bf16_f32 v97, v223, v126
	v_cvt_pk_bf16_f32 v98, v241, v242
	v_cvt_pk_bf16_f32 v99, v243, v240
	v_mfma_f32_32x32x16_bf16 v[32:47], v[144:147], v[116:119], v[32:47]
	v_exp_f32_e32 v125, v104
	v_exp_f32_e32 v104, v105
	v_exp_f32_e32 v105, v106
	v_exp_f32_e32 v124, v107
	v_add_f32_e32 v106, v162, v156
	v_add_f32_e32 v107, v163, v157
	v_add_f32_e32 v168, v184, v168
	v_add_f32_e32 v169, v185, v169
	v_add_f32_e32 v106, v170, v106
	v_add_f32_e32 v107, v171, v107
	v_add_f32_e32 v168, v188, v168
	v_add_f32_e32 v169, v189, v169
	v_add_f32_e32 v106, v186, v106
	v_add_f32_e32 v107, v187, v107
	v_add_f32_e32 v168, v190, v168
	v_add_f32_e32 v169, v191, v169
	v_add_f32_e32 v106, v106, v192
	v_add_f32_e32 v107, v107, v193
	s_waitcnt lgkmcnt(0)
	v_mfma_f32_32x32x16_bf16 v[0:15], v[180:183], v[112:115], v[0:15]
	v_add_f32_e64 v168, v168, v194
	v_add_f32_e64 v169, v169, v195
	v_add_f32_e64 v106, v228, v106
	v_add_f32_e64 v107, v229, v107
	v_add_f32_e64 v168, v230, v168
	v_add_f32_e64 v169, v231, v169
	v_add_f32_e32 v106, v232, v106
	v_add_f32_e32 v107, v233, v107
	v_add_f32_e32 v168, v234, v168
	v_add_f32_e32 v169, v235, v169
	v_add_f32_e32 v106, v236, v106
	v_add_f32_e32 v107, v237, v107
	v_add_u32_e32 v219, 0, v213
	v_mfma_f32_32x32x16_bf16 v[64:79], v[224:227], v[136:139], v[64:79]
	v_add_u32_e32 v220, s11, v213
	v_add_f32_e64 v168, v238, v168
	v_add_f32_e64 v169, v239, v169
	v_add_f32_e64 v106, v106, v126
	v_add_f32_e64 v107, v107, v127
	v_exp_f32_e32 v127, v108
	v_exp_f32_e32 v108, v109
	v_exp_f32_e32 v109, v110
	v_exp_f32_e32 v126, v111
	v_mfma_f32_32x32x16_bf16 v[16:31], v[174:177], v[112:115], v[16:31]
	ds_read_b128 v[100:103], v219 offset:61440
	ds_read_b128 v[120:123], v220
	v_add_f32_e64 v168, v168, v222
	v_add_f32_e64 v169, v169, v223
	v_add_f32_e64 v106, v240, v106
	v_add_f32_e64 v107, v241, v107
	v_add_f32_e32 v168, v242, v168
	v_add_f32_e32 v169, v243, v169
	v_add_f32_e32 v106, v124, v106
	v_add_f32_e32 v107, v125, v107
	v_add_f32_e32 v168, v104, v168
	v_add_f32_e32 v169, v105, v169
	v_mfma_f32_32x32x16_bf16 v[32:47], v[144:147], v[112:115], v[32:47]
	v_add_f32_e64 v162, v108, v168
	v_add_f32_e64 v163, v109, v169
	v_add_f32_e64 v156, v126, v106
	v_add_f32_e64 v157, v127, v107
	v_cvt_pk_bf16_f32 v104, v125, v104
	v_cvt_pk_bf16_f32 v105, v105, v124
	v_cvt_pk_bf16_f32 v106, v127, v108
	v_cvt_pk_bf16_f32 v107, v109, v126
	s_waitcnt lgkmcnt(0)
	v_mfma_f32_32x32x16_bf16 v[16:31], v[100:103], v[96:99], v[16:31]
	v_add_u32_e32 v168, 0, v214
	v_add_u32_e32 v169, s11, v214
	ds_read_b128 v[100:103], v168 offset:61440
	ds_read_b128 v[108:111], v169
	v_mfma_f32_32x32x16_bf16 v[0:15], v[120:123], v[96:99], v[0:15]
	s_waitcnt lgkmcnt(0)
	v_mfma_f32_32x32x16_bf16 v[16:31], v[100:103], v[104:107], v[16:31]
	v_mfma_f32_32x32x16_bf16 v[0:15], v[108:111], v[104:107], v[0:15]
	s_waitcnt vmcnt(2)
	s_waitcnt lgkmcnt(0)
	s_barrier
	s_add_i32 s9, s9, 4
	v_lshl_add_u64 v[158:159], v[158:159], 0, s[64:65]
	s_cmpk_lt_u32 s9, 0xf8
	v_lshl_add_u64 v[160:161], v[160:161], 0, s[66:67]
	s_cbranch_scc1 .LBB0_541
; #define DMA_WAIT(keep) do { if (keep) { if (TYPE == 0 && wid < 4) asm volatile("s_waitcnt vmcnt(3)" ::: "memory"); else asm volatile("s_waitcnt vmcnt(2)" ::: "memory"); } \
;     else asm volatile("s_waitcnt vmcnt(0)" ::: "memory"); } while (0)
; #define BAR() do { asm volatile("s_waitcnt lgkmcnt(0)" ::: "memory"); __builtin_amdgcn_s_barrier(); asm volatile("" ::: "memory"); } while (0)
; #define QKR(d0, K0, K1, SOFF) do { if ((d0) < 4) { K0 = *(const bf16x8*)(lds + (SOFF) + koff[(d0) & 3]); K1 = *(const bf16x8*)(lds + (SOFF) + 32 * 128 + koff[(d0) & 3]); } \
;     else if ((d0) < NQK) { K0 = *(const bf16x8*)(lds + (SOFF) + roff[(d0) & 1]); K1 = *(const bf16x8*)(lds + (SOFF) + 32 * 64 + roff[(d0) & 1]); } } while (0)
; #define QKM(N0, N1, d0, K0, K1) do { if ((d0) == 0) { N0 = MFMA(K0, qf[0], negm); N1 = MFMA(K1, qf[0], negm); } \
;     else if ((d0) < NQK) { N0 = MFMA(K0, qf[(d0) < NQK ? (d0) : 0], N0); N1 = MFMA(K1, qf[(d0) < NQK ? (d0) : 0], N1); } } while (0)
; template <int TYPE, bool FIXREF>
; DI void attn_dense_unit(const Params& p, int layer, int head, int qb, char* lds, float bref) {
;     ...
;   constexpr int R0 = 0, R1 = ATT_STAGE, R2 = 2 * ATT_STAGE, R3 = 3 * ATT_STAGE;
;   f32x16 sA0, sA1, sB0, sB1;
;   DMA(0, R0); DMA(1, R1); DMA(2, R2); DMA_WAIT(true); BAR();
;   if (FIXREF) { m_run = bref;
; #pragma unroll
;     for (int i = 0; i < 16; ++i) negm[i] = -bref; }
;   { bf16x8 ka0, ka1;
; #pragma unroll
;     for (int d0 = 0; d0 < NQK; ++d0) { QKR(d0, ka0, ka1, R0); QKM(sA0, sA1, d0, ka0, ka1); } }
;   if (!FIXREF) { float mx0; ROWMAX(sA0, sA1, mx0); m_run = mx0;
; #pragma unroll
;     for (int i = 0; i < 16; ++i) { sA0[i] -= mx0; sA1[i] -= mx0; negm[i] = -mx0; } }
;   for (int t = 0; t < NT - 4; t += 4) {
;     STEP(sA0, sA1, sB0, sB1, t, true, true, R0, R1, R3);
;     STEP(sB0, sB1, sA0, sA1, t + 1, true, true, R1, R2, R0);
;     STEP(sA0, sA1, sB0, sB1, t + 2, true, true, R2, R3, R1);
;     STEP(sB0, sB1, sA0, sA1, t + 3, true, true, R3, R0, R2);
;   }
;   STEP(sA0, sA1, sB0, sB1, NT - 4, true, true, R0, R1, R3);
;   STEP(sB0, sB1, sA0, sA1, NT - 3, true, false, R1, R2, R0);
;   STEP(sA0, sA1, sB0, sB1, NT - 2, true, false, R2, R3, R1);
;   STEP(sB0, sB1, sA0, sA1, NT - 1, false, false, R3, R0, R2);
	s_mov_b64 s[0:1], 0xef10000
	s_mov_b32 m0, s10
	v_lshl_add_u64 v[96:97], v[154:155], 0, s[0:1]
	s_mov_b64 s[0:1], 0x7f80
	global_load_lds_dwordx4 v[96:97], off
	v_lshl_add_u64 v[96:97], v[152:153], 0, s[0:1]
	s_mov_b32 m0, s8
	s_mov_b64 s[88:89], 0x17618300
	global_load_lds_dwordx4 v[96:97], off
	ds_read_b128 v[96:99], v201 offset:20480
	ds_read_b128 v[144:147], v201 offset:24576
	s_mov_b64 s[62:63], 0x33ba200
	ds_read_b128 v[100:103], v202 offset:20480
	ds_read_b128 v[152:155], v202 offset:24576
	v_exp_f32_e32 v170, v80
	v_exp_f32_e32 v171, v81
	v_exp_f32_e32 v172, v82
	v_exp_f32_e32 v175, v83
	s_waitcnt lgkmcnt(0)
	v_mfma_f32_32x32x16_bf16 v[112:127], v[96:99], v[132:135], v[48:63]
	ds_read_b128 v[80:83], v204 offset:20480
	ds_read_b128 v[158:161], v204 offset:24576
	v_exp_f32_e32 v84, v84
	v_exp_f32_e32 v85, v85
	v_exp_f32_e32 v86, v86
	v_exp_f32_e32 v87, v87
	v_mfma_f32_32x32x16_bf16 v[112:127], v[100:103], v[128:131], v[112:127]
	v_cvt_pk_bf16_f32 v174, v170, v171
	v_cvt_pk_bf16_f32 v175, v172, v175
	v_cvt_pk_bf16_f32 v176, v84, v85
	v_cvt_pk_bf16_f32 v177, v86, v87
	v_mfma_f32_32x32x16_bf16 v[96:111], v[144:147], v[132:135], v[48:63]
	ds_read_b128 v[84:87], v203 offset:20480
	ds_read_b128 v[144:147], v203 offset:24576
	s_waitcnt lgkmcnt(0)
	v_mfma_f32_32x32x16_bf16 v[112:127], v[80:83], v[140:143], v[112:127]
	v_exp_f32_e32 v80, v88
	v_exp_f32_e32 v81, v89
	v_exp_f32_e32 v82, v90
	v_exp_f32_e32 v83, v91
	v_mfma_f32_32x32x16_bf16 v[112:127], v[84:87], v[136:139], v[112:127]
	v_exp_f32_e32 v84, v92
	v_exp_f32_e32 v85, v93
	v_exp_f32_e32 v86, v94
	v_exp_f32_e32 v87, v95
	v_cvt_pk_bf16_f32 v180, v80, v81
	v_cvt_pk_bf16_f32 v181, v82, v83
	v_cvt_pk_bf16_f32 v182, v84, v85
	v_mfma_f32_32x32x16_bf16 v[96:111], v[152:155], v[128:131], v[96:111]
	v_cvt_pk_bf16_f32 v183, v86, v87
	ds_read_b128 v[80:83], v206 offset:8192
	ds_read_b128 v[84:87], v206 offset:12288
	v_mfma_f32_32x32x16_bf16 v[96:111], v[158:161], v[140:143], v[96:111]
	s_waitcnt lgkmcnt(0)
	v_mfma_f32_32x32x16_bf16 v[0:15], v[84:87], v[174:177], v[0:15]
	ds_read_b128 v[88:91], v205 offset:8192
	ds_read_b128 v[92:95], v205 offset:12288
	v_exp_f32_e32 v153, v64
	v_exp_f32_e32 v171, v65
	v_exp_f32_e32 v184, v66
	v_exp_f32_e32 v152, v67
	v_exp_f32_e32 v170, v68
	v_exp_f32_e32 v172, v69
	v_exp_f32_e32 v186, v70
	v_exp_f32_e32 v154, v71
	v_mfma_f32_32x32x16_bf16 v[16:31], v[80:83], v[174:177], v[16:31]
	v_cvt_pk_bf16_f32 v64, v153, v171
	v_cvt_pk_bf16_f32 v65, v184, v152
	v_cvt_pk_bf16_f32 v66, v170, v172
	v_cvt_pk_bf16_f32 v67, v186, v154
	s_waitcnt lgkmcnt(0)
	v_mfma_f32_32x32x16_bf16 v[0:15], v[92:95], v[180:183], v[0:15]
	ds_read_b128 v[68:71], v200 offset:8192
	ds_read_b128 v[190:193], v200 offset:12288
	v_exp_f32_e32 v185, v72
	v_exp_f32_e32 v187, v73
	v_exp_f32_e32 v189, v74
	v_exp_f32_e32 v158, v75
	v_exp_f32_e32 v155, v76
	v_exp_f32_e32 v188, v77
	v_exp_f32_e32 v194, v78
	v_exp_f32_e32 v160, v79
	v_mfma_f32_32x32x16_bf16 v[96:111], v[144:147], v[136:139], v[96:111]
	v_cvt_pk_bf16_f32 v72, v185, v187
	v_cvt_pk_bf16_f32 v73, v189, v158
	v_cvt_pk_bf16_f32 v74, v155, v188
	v_cvt_pk_bf16_f32 v75, v194, v160
	v_mfma_f32_32x32x16_bf16 v[16:31], v[88:91], v[180:183], v[16:31]
	ds_read_b128 v[76:79], v151 offset:8192
	ds_read_b128 v[208:211], v151 offset:12288
	s_waitcnt lgkmcnt(0)
	v_mfma_f32_32x32x16_bf16 v[16:31], v[68:71], v[64:67], v[16:31]
	v_mfma_f32_32x32x16_bf16 v[16:31], v[76:79], v[72:75], v[16:31]
	s_waitcnt vmcnt(2)
	s_waitcnt lgkmcnt(0)
	s_barrier
	ds_read_b128 v[68:71], v201 offset:40960
	ds_read_b128 v[222:225], v201 offset:45056
	v_mfma_f32_32x32x16_bf16 v[0:15], v[190:193], v[64:67], v[0:15]
	v_mov_b64_e32 v[146:147], s[38:39]
	v_mov_b64_e32 v[144:145], s[36:37]
	v_exp_f32_e32 v159, v112
	v_exp_f32_e32 v161, v113
	v_exp_f32_e32 v195, v114
	v_exp_f32_e32 v207, v115
	v_mfma_f32_32x32x16_bf16 v[0:15], v[208:211], v[72:75], v[0:15]
	v_mfma_f32_32x32x16_bf16 v[32:47], v[144:147], v[174:177], v[32:47]
	ds_read_b128 v[64:67], v202 offset:40960
	ds_read_b128 v[174:177], v202 offset:45056
	s_waitcnt lgkmcnt(0)
	v_mfma_f32_32x32x16_bf16 v[80:95], v[68:71], v[132:135], v[48:63]
	ds_read_b128 v[112:115], v204 offset:40960
	ds_read_b128 v[190:193], v204 offset:45056
	v_exp_f32_e32 v116, v116
	v_exp_f32_e32 v117, v117
	v_exp_f32_e32 v118, v118
	v_exp_f32_e32 v119, v119
	v_mfma_f32_32x32x16_bf16 v[80:95], v[64:67], v[128:131], v[80:95]
	v_cvt_pk_bf16_f32 v208, v159, v161
	v_cvt_pk_bf16_f32 v209, v195, v207
	v_cvt_pk_bf16_f32 v210, v116, v117
	v_cvt_pk_bf16_f32 v211, v118, v119
	v_mfma_f32_32x32x16_bf16 v[64:79], v[222:225], v[132:135], v[48:63]
	s_waitcnt lgkmcnt(0)
	v_mfma_f32_32x32x16_bf16 v[80:95], v[112:115], v[140:143], v[80:95]
	ds_read_b128 v[112:115], v203 offset:40960
	ds_read_b128 v[222:225], v203 offset:45056
	v_exp_f32_e32 v116, v120
	v_exp_f32_e32 v117, v121
	v_exp_f32_e32 v118, v122
	v_exp_f32_e32 v119, v123
	v_mfma_f32_32x32x16_bf16 v[32:47], v[144:147], v[180:183], v[32:47]
	s_waitcnt lgkmcnt(0)
	v_mfma_f32_32x32x16_bf16 v[80:95], v[112:115], v[136:139], v[80:95]
	v_exp_f32_e32 v114, v126
	v_exp_f32_e32 v115, v127
	v_exp_f32_e32 v112, v124
	v_exp_f32_e32 v113, v125
	v_cvt_pk_bf16_f32 v120, v116, v117
	v_cvt_pk_bf16_f32 v123, v114, v115
	ds_read_b128 v[114:117], v206 offset:28672
	ds_read_b128 v[124:127], v206 offset:32768
	v_mfma_f32_32x32x16_bf16 v[64:79], v[174:177], v[128:131], v[64:79]
	v_cvt_pk_bf16_f32 v121, v118, v119
	v_cvt_pk_bf16_f32 v122, v112, v113
	v_mfma_f32_32x32x16_bf16 v[64:79], v[190:193], v[140:143], v[64:79]
	s_waitcnt lgkmcnt(0)
; #define DMA_WAIT(keep) do { if (keep) { if (TYPE == 0 && wid < 4) asm volatile("s_waitcnt vmcnt(3)" ::: "memory"); else asm volatile("s_waitcnt vmcnt(2)" ::: "memory"); } \
;     else asm volatile("s_waitcnt vmcnt(0)" ::: "memory"); } while (0)
; #define BAR() do { asm volatile("s_waitcnt lgkmcnt(0)" ::: "memory"); __builtin_amdgcn_s_barrier(); asm volatile("" ::: "memory"); } while (0)
; #define QKR(d0, K0, K1, SOFF) do { if ((d0) < 4) { K0 = *(const bf16x8*)(lds + (SOFF) + koff[(d0) & 3]); K1 = *(const bf16x8*)(lds + (SOFF) + 32 * 128 + koff[(d0) & 3]); } \
;     else if ((d0) < NQK) { K0 = *(const bf16x8*)(lds + (SOFF) + roff[(d0) & 1]); K1 = *(const bf16x8*)(lds + (SOFF) + 32 * 64 + roff[(d0) & 1]); } } while (0)
; #define QKM(N0, N1, d0, K0, K1) do { if ((d0) == 0) { N0 = MFMA(K0, qf[0], negm); N1 = MFMA(K1, qf[0], negm); } \
;     else if ((d0) < NQK) { N0 = MFMA(K0, qf[(d0) < NQK ? (d0) : 0], N0); N1 = MFMA(K1, qf[(d0) < NQK ? (d0) : 0], N1); } } while (0)
; template <int TYPE, bool FIXREF>
; DI void attn_dense_unit(const Params& p, int layer, int head, int qb, char* lds, float bref) {
;     ...
;   constexpr int R0 = 0, R1 = ATT_STAGE, R2 = 2 * ATT_STAGE, R3 = 3 * ATT_STAGE;
;   f32x16 sA0, sA1, sB0, sB1;
;   DMA(0, R0); DMA(1, R1); DMA(2, R2); DMA_WAIT(true); BAR();
;   if (FIXREF) { m_run = bref;
; #pragma unroll
;     for (int i = 0; i < 16; ++i) negm[i] = -bref; }
;   { bf16x8 ka0, ka1;
; #pragma unroll
;     for (int d0 = 0; d0 < NQK; ++d0) { QKR(d0, ka0, ka1, R0); QKM(sA0, sA1, d0, ka0, ka1); } }
;   if (!FIXREF) { float mx0; ROWMAX(sA0, sA1, mx0); m_run = mx0;
; #pragma unroll
;     for (int i = 0; i < 16; ++i) { sA0[i] -= mx0; sA1[i] -= mx0; negm[i] = -mx0; } }
;   for (int t = 0; t < NT - 4; t += 4) {
;     STEP(sA0, sA1, sB0, sB1, t, true, true, R0, R1, R3);
;     STEP(sB0, sB1, sA0, sA1, t + 1, true, true, R1, R2, R0);
;     STEP(sA0, sA1, sB0, sB1, t + 2, true, true, R2, R3, R1);
;     STEP(sB0, sB1, sA0, sA1, t + 3, true, true, R3, R0, R2);
;   }
;   STEP(sA0, sA1, sB0, sB1, NT - 4, true, true, R0, R1, R3);
;   STEP(sB0, sB1, sA0, sA1, NT - 3, true, false, R1, R2, R0);
;   STEP(sA0, sA1, sB0, sB1, NT - 2, true, false, R2, R3, R1);
;   STEP(sB0, sB1, sA0, sA1, NT - 1, false, false, R3, R0, R2);
	v_mfma_f32_32x32x16_bf16 v[0:15], v[124:127], v[208:211], v[0:15]
	ds_read_b128 v[174:177], v205 offset:28672
	ds_read_b128 v[180:183], v205 offset:32768
	v_exp_f32_e32 v159, v96
	v_exp_f32_e32 v195, v97
	v_exp_f32_e32 v207, v98
	v_exp_f32_e32 v112, v99
	v_exp_f32_e32 v161, v100
	v_exp_f32_e32 v221, v101
	v_mfma_f32_32x32x16_bf16 v[16:31], v[114:117], v[208:211], v[16:31]
	v_exp_f32_e32 v226, v102
	v_exp_f32_e32 v114, v103
	v_cvt_pk_bf16_f32 v124, v159, v195
	v_cvt_pk_bf16_f32 v125, v207, v112
	v_cvt_pk_bf16_f32 v126, v161, v221
	v_cvt_pk_bf16_f32 v127, v226, v114
	s_waitcnt lgkmcnt(0)
	v_mfma_f32_32x32x16_bf16 v[0:15], v[180:183], v[120:123], v[0:15]
	ds_read_b128 v[96:99], v200 offset:28672
	ds_read_b128 v[180:183], v200 offset:32768
	v_exp_f32_e32 v113, v104
	v_exp_f32_e32 v227, v105
	v_exp_f32_e32 v228, v106
	v_exp_f32_e32 v116, v107
	v_exp_f32_e32 v115, v108
	v_exp_f32_e32 v229, v109
	v_exp_f32_e32 v230, v110
	v_exp_f32_e32 v118, v111
	v_mfma_f32_32x32x16_bf16 v[64:79], v[222:225], v[136:139], v[64:79]
	v_cvt_pk_bf16_f32 v190, v113, v227
	v_cvt_pk_bf16_f32 v191, v228, v116
	v_cvt_pk_bf16_f32 v192, v115, v229
	v_cvt_pk_bf16_f32 v193, v230, v118
	v_mfma_f32_32x32x16_bf16 v[16:31], v[174:177], v[120:123], v[16:31]
	ds_read_b128 v[100:103], v151 offset:28672
	ds_read_b128 v[174:177], v151 offset:32768
	s_waitcnt lgkmcnt(0)
	v_mfma_f32_32x32x16_bf16 v[16:31], v[96:99], v[124:127], v[16:31]
	v_mfma_f32_32x32x16_bf16 v[16:31], v[100:103], v[190:193], v[16:31]
	s_waitcnt vmcnt(0)
	s_waitcnt lgkmcnt(0)
	s_barrier
	ds_read_b128 v[222:225], v201 offset:61440
	ds_read_b128 v[212:215], v215
	v_mfma_f32_32x32x16_bf16 v[0:15], v[180:183], v[124:127], v[0:15]
	ds_read_b128 v[124:127], v202 offset:61440
	ds_read_b128 v[180:183], v216
	v_exp_f32_e32 v117, v80
	v_exp_f32_e32 v119, v81
	v_exp_f32_e32 v201, v82
	v_exp_f32_e32 v202, v83
	v_mfma_f32_32x32x16_bf16 v[0:15], v[174:177], v[190:193], v[0:15]
	s_waitcnt lgkmcnt(0)
	v_mfma_f32_32x32x16_bf16 v[96:111], v[222:225], v[132:135], v[48:63]
	v_mfma_f32_32x32x16_bf16 v[32:47], v[144:147], v[208:211], v[32:47]
	ds_read_b128 v[80:83], v204 offset:61440
	ds_read_b128 v[174:177], v217
	v_mfma_f32_32x32x16_bf16 v[96:111], v[124:127], v[128:131], v[96:111]
	v_exp_f32_e32 v124, v84
	v_exp_f32_e32 v125, v85
	v_exp_f32_e32 v126, v86
	v_exp_f32_e32 v87, v87
	v_cvt_pk_bf16_f32 v84, v117, v119
	v_cvt_pk_bf16_f32 v85, v201, v202
	v_cvt_pk_bf16_f32 v86, v124, v125
	v_cvt_pk_bf16_f32 v87, v126, v87
	v_mfma_f32_32x32x16_bf16 v[48:63], v[212:215], v[132:135], v[48:63]
	s_waitcnt lgkmcnt(0)
	v_mfma_f32_32x32x16_bf16 v[96:111], v[80:83], v[140:143], v[96:111]
	ds_read_b128 v[80:83], v203 offset:61440
	ds_read_b128 v[124:127], v218
	v_exp_f32_e32 v88, v88
	v_exp_f32_e32 v89, v89
	v_exp_f32_e32 v90, v90
	v_exp_f32_e32 v91, v91
	v_mfma_f32_32x32x16_bf16 v[32:47], v[144:147], v[120:123], v[32:47]
	s_waitcnt lgkmcnt(0)
	v_mfma_f32_32x32x16_bf16 v[96:111], v[80:83], v[136:139], v[96:111]
	v_exp_f32_e32 v82, v92
	v_exp_f32_e32 v83, v93
	v_exp_f32_e32 v92, v94
	v_exp_f32_e32 v93, v95
	v_cvt_pk_bf16_f32 v80, v88, v89
	v_cvt_pk_bf16_f32 v81, v90, v91
	v_cvt_pk_bf16_f32 v82, v82, v83
	v_mfma_f32_32x32x16_bf16 v[48:63], v[180:183], v[128:131], v[48:63]
	v_cvt_pk_bf16_f32 v83, v92, v93
	ds_read_b128 v[88:91], v206 offset:49152
	ds_read_b128 v[92:95], v206 offset:53248
	v_mfma_f32_32x32x16_bf16 v[48:63], v[174:177], v[140:143], v[48:63]
	s_waitcnt lgkmcnt(0)
	v_mfma_f32_32x32x16_bf16 v[0:15], v[92:95], v[84:87], v[0:15]
	ds_read_b128 v[120:123], v205 offset:49152
	ds_read_b128 v[128:131], v205 offset:53248
	v_exp_f32_e32 v117, v64
	v_exp_f32_e32 v132, v65
	v_exp_f32_e32 v133, v66
	v_exp_f32_e32 v64, v67
	v_exp_f32_e32 v119, v68
	v_exp_f32_e32 v134, v69
	v_exp_f32_e32 v135, v70
	v_exp_f32_e32 v66, v71
	v_mfma_f32_32x32x16_bf16 v[16:31], v[88:91], v[84:87], v[16:31]
	v_cvt_pk_bf16_f32 v88, v117, v132
	v_cvt_pk_bf16_f32 v89, v133, v64
	v_cvt_pk_bf16_f32 v90, v119, v134
	v_cvt_pk_bf16_f32 v91, v135, v66
	s_waitcnt lgkmcnt(0)
	v_mfma_f32_32x32x16_bf16 v[0:15], v[128:131], v[80:83], v[0:15]
	ds_read_b128 v[92:95], v200 offset:49152
	ds_read_b128 v[128:131], v200 offset:53248
	v_exp_f32_e32 v65, v72
	v_exp_f32_e32 v140, v73
	v_exp_f32_e32 v141, v74
	v_exp_f32_e32 v68, v75
	v_exp_f32_e32 v67, v76
	v_exp_f32_e32 v70, v79
	v_mfma_f32_32x32x16_bf16 v[48:63], v[124:127], v[136:139], v[48:63]
	v_exp_f32_e32 v124, v77
	v_exp_f32_e32 v125, v78
	v_cvt_pk_bf16_f32 v72, v65, v140
	v_cvt_pk_bf16_f32 v73, v141, v68
	v_cvt_pk_bf16_f32 v74, v67, v124
	v_cvt_pk_bf16_f32 v75, v125, v70
	v_mfma_f32_32x32x16_bf16 v[16:31], v[120:123], v[80:83], v[16:31]
	ds_read_b128 v[76:79], v151 offset:49152
	ds_read_b128 v[120:123], v151 offset:53248
	s_waitcnt lgkmcnt(0)
	v_mfma_f32_32x32x16_bf16 v[16:31], v[92:95], v[88:91], v[16:31]
	v_mfma_f32_32x32x16_bf16 v[16:31], v[76:79], v[72:75], v[16:31]
	s_waitcnt vmcnt(0)
	s_waitcnt lgkmcnt(0)
	s_barrier
; #define DMA_WAIT(keep) do { if (keep) { if (TYPE == 0 && wid < 4) asm volatile("s_waitcnt vmcnt(3)" ::: "memory"); else asm volatile("s_waitcnt vmcnt(2)" ::: "memory"); } \
;     else asm volatile("s_waitcnt vmcnt(0)" ::: "memory"); } while (0)
; #define BAR() do { asm volatile("s_waitcnt lgkmcnt(0)" ::: "memory"); __builtin_amdgcn_s_barrier(); asm volatile("" ::: "memory"); } while (0)
; #define QKR(d0, K0, K1, SOFF) do { if ((d0) < 4) { K0 = *(const bf16x8*)(lds + (SOFF) + koff[(d0) & 3]); K1 = *(const bf16x8*)(lds + (SOFF) + 32 * 128 + koff[(d0) & 3]); } \
;     else if ((d0) < NQK) { K0 = *(const bf16x8*)(lds + (SOFF) + roff[(d0) & 1]); K1 = *(const bf16x8*)(lds + (SOFF) + 32 * 64 + roff[(d0) & 1]); } } while (0)
; #define QKM(N0, N1, d0, K0, K1) do { if ((d0) == 0) { N0 = MFMA(K0, qf[0], negm); N1 = MFMA(K1, qf[0], negm); } \
;     else if ((d0) < NQK) { N0 = MFMA(K0, qf[(d0) < NQK ? (d0) : 0], N0); N1 = MFMA(K1, qf[(d0) < NQK ? (d0) : 0], N1); } } while (0)
; template <int TYPE, bool FIXREF>
; DI void attn_dense_unit(const Params& p, int layer, int head, int qb, char* lds, float bref) {
;     ...
;   constexpr int R0 = 0, R1 = ATT_STAGE, R2 = 2 * ATT_STAGE, R3 = 3 * ATT_STAGE;
;   f32x16 sA0, sA1, sB0, sB1;
;   DMA(0, R0); DMA(1, R1); DMA(2, R2); DMA_WAIT(true); BAR();
;   if (FIXREF) { m_run = bref;
; #pragma unroll
;     for (int i = 0; i < 16; ++i) negm[i] = -bref; }
;   { bf16x8 ka0, ka1;
; #pragma unroll
;     for (int d0 = 0; d0 < NQK; ++d0) { QKR(d0, ka0, ka1, R0); QKM(sA0, sA1, d0, ka0, ka1); } }
;   if (!FIXREF) { float mx0; ROWMAX(sA0, sA1, mx0); m_run = mx0;
; #pragma unroll
;     for (int i = 0; i < 16; ++i) { sA0[i] -= mx0; sA1[i] -= mx0; negm[i] = -mx0; } }
;   for (int t = 0; t < NT - 4; t += 4) {
;     STEP(sA0, sA1, sB0, sB1, t, true, true, R0, R1, R3);
;     STEP(sB0, sB1, sA0, sA1, t + 1, true, true, R1, R2, R0);
;     STEP(sA0, sA1, sB0, sB1, t + 2, true, true, R2, R3, R1);
;     STEP(sB0, sB1, sA0, sA1, t + 3, true, true, R3, R0, R2);
;   }
;   STEP(sA0, sA1, sB0, sB1, NT - 4, true, true, R0, R1, R3);
;   STEP(sB0, sB1, sA0, sA1, NT - 3, true, false, R1, R2, R0);
;   STEP(sA0, sA1, sB0, sB1, NT - 2, true, false, R2, R3, R1);
;   STEP(sB0, sB1, sA0, sA1, NT - 1, false, false, R3, R0, R2);
;   lsum += ls0 + ls1 + ls2;
;   const float l = (NONES > 0 ? la[0] : 0.f) + lsum + __shfl_xor(lsum, 32);
	v_mfma_f32_32x32x16_bf16 v[0:15], v[128:131], v[88:91], v[0:15]
	v_exp_f32_e32 v69, v96
	v_exp_f32_e32 v71, v97
	v_exp_f32_e32 v77, v98
	v_exp_f32_e32 v78, v99
	v_mfma_f32_32x32x16_bf16 v[32:47], v[144:147], v[84:87], v[32:47]
	v_exp_f32_e32 v79, v100
	v_exp_f32_e32 v84, v101
	v_exp_f32_e32 v85, v102
	v_exp_f32_e32 v86, v103
	v_mfma_f32_32x32x16_bf16 v[32:47], v[144:147], v[80:83], v[32:47]
	v_cvt_pk_bf16_f32 v76, v69, v71
	v_cvt_pk_bf16_f32 v77, v77, v78
	v_cvt_pk_bf16_f32 v78, v79, v84
	v_cvt_pk_bf16_f32 v79, v85, v86
	v_exp_f32_e32 v69, v104
	v_exp_f32_e32 v71, v105
	v_exp_f32_e32 v80, v106
	v_exp_f32_e32 v81, v107
	v_exp_f32_e32 v82, v108
	v_exp_f32_e32 v83, v109
	v_exp_f32_e32 v84, v110
	v_exp_f32_e32 v85, v111
	v_mfma_f32_32x32x16_bf16 v[0:15], v[120:123], v[72:75], v[0:15]
	v_cvt_pk_bf16_f32 v73, v80, v81
	v_cvt_pk_bf16_f32 v74, v82, v83
	v_cvt_pk_bf16_f32 v75, v84, v85
	ds_read_b128 v[80:83], v166 offset:61440
	ds_read_b128 v[84:87], v167
	v_cvt_pk_bf16_f32 v72, v69, v71
	s_waitcnt lgkmcnt(0)
	v_mfma_f32_32x32x16_bf16 v[0:15], v[84:87], v[76:79], v[0:15]
	ds_read_b128 v[84:87], v164 offset:61440
	ds_read_b128 v[88:91], v165
	v_mfma_f32_32x32x16_bf16 v[16:31], v[80:83], v[76:79], v[16:31]
	v_exp_f32_e32 v69, v48
	v_add_f32_e32 v48, v163, v184
	v_add_f32_e32 v48, v186, v48
	v_add_f32_e32 v48, v189, v48
	v_add_f32_e32 v48, v194, v48
	v_add_f32_e32 v48, v48, v207
	v_add_f32_e32 v48, v226, v48
	v_add_f32_e32 v48, v228, v48
	v_add_f32_e32 v48, v230, v48
	s_waitcnt lgkmcnt(0)
	v_mfma_f32_32x32x16_bf16 v[0:15], v[88:91], v[72:75], v[0:15]
	v_exp_f32_e32 v88, v59
	v_exp_f32_e32 v59, v50
	v_add_f32_e32 v48, v48, v133
	v_exp_f32_e32 v71, v52
	v_exp_f32_e32 v52, v53
	v_exp_f32_e32 v53, v54
	v_add_f32_e32 v48, v135, v48
	v_mfma_f32_32x32x16_bf16 v[16:31], v[84:87], v[72:75], v[16:31]
	v_exp_f32_e32 v85, v56
	v_exp_f32_e32 v56, v58
	v_add_f32_e32 v48, v141, v48
	v_exp_f32_e32 v58, v62
	v_add_f32_e32 v48, v125, v48
	v_add_f32_e32 v48, v48, v59
	v_add_f32_e32 v48, v53, v48
	v_add_f32_e32 v48, v56, v48
	v_add_f32_e32 v91, v58, v48
	v_add_f32_e32 v48, v162, v171
	v_add_f32_e32 v48, v172, v48
	v_add_f32_e32 v48, v187, v48
	v_add_f32_e32 v48, v188, v48
	v_add_f32_e32 v48, v48, v195
	v_add_f32_e32 v48, v221, v48
	v_add_f32_e32 v48, v227, v48
	v_add_f32_e32 v48, v229, v48
	v_exp_f32_e32 v86, v55
	v_exp_f32_e32 v55, v49
	v_add_f32_e32 v48, v48, v132
	v_add_f32_e32 v48, v134, v48
	v_exp_f32_e32 v54, v57
	v_add_f32_e32 v48, v140, v48
	v_exp_f32_e32 v57, v61
	v_add_f32_e32 v48, v124, v48
	v_mfma_f32_32x32x16_bf16 v[32:47], v[144:147], v[76:79], v[32:47]
	v_add_f32_e32 v48, v48, v55
	v_add_f32_e32 v48, v52, v48
	v_add_f32_e32 v48, v54, v48
	ds_read_b128 v[80:83], v219 offset:61440
	ds_read_b128 v[92:95], v220
	v_add_f32_e32 v89, v57, v48
	v_add_f32_e32 v48, v157, v153
	v_exp_f32_e32 v84, v51
	v_exp_f32_e32 v90, v63
	v_exp_f32_e32 v87, v60
	v_add_f32_e32 v153, v170, v48
	v_mov_b32_e32 v157, v185
	v_pk_add_f32 v[48:49], v[156:157], v[152:153]
	v_mfma_f32_32x32x16_bf16 v[32:47], v[144:147], v[72:75], v[32:47]
	v_add_f32_e64 v48, v154, v48
	v_add_f32_e64 v49, v155, v49
	v_add_f32_e64 v48, v158, v48
	v_add_f32_e64 v49, v159, v49
	v_add_f32_e64 v50, v160, v48
	v_add_f32_e64 v51, v161, v49
	s_nop 5
	v_cvt_pk_bf16_f32 v34, v69, v55
	v_cvt_pk_bf16_f32 v35, v59, v84
	v_cvt_pk_bf16_f32 v36, v71, v52
	v_cvt_pk_bf16_f32 v37, v53, v86
	v_cvt_pk_bf16_f32 v38, v85, v54
	v_cvt_pk_bf16_f32 v39, v56, v88
	v_cvt_pk_bf16_f32 v40, v87, v57
	v_cvt_pk_bf16_f32 v41, v58, v90
	s_waitcnt lgkmcnt(0)
	v_mfma_f32_32x32x16_bf16 v[0:15], v[92:95], v[34:37], v[0:15]
	ds_read_b128 v[42:45], v168 offset:61440
	ds_read_b128 v[46:49], v169
	v_mfma_f32_32x32x16_bf16 v[16:31], v[80:83], v[34:37], v[16:31]
	s_waitcnt lgkmcnt(0)
	v_mfma_f32_32x32x16_bf16 v[0:15], v[46:49], v[38:41], v[0:15]
	v_mfma_f32_32x32x16_bf16 v[16:31], v[42:45], v[38:41], v[16:31]
	v_add_f32_e64 v34, v50, v112
	v_add_f32_e64 v35, v51, v113
	v_lshlrev_b32_e32 v172, 1, v150
	v_add_f32_e64 v34, v114, v34
	v_add_f32_e64 v35, v115, v35
	s_waitcnt vmcnt(0)
	s_waitcnt lgkmcnt(0)
	s_barrier
; DI unsigned pk2(float lo, float hi) { f32x2 v = {lo, hi}; bf16x2_t b = __builtin_convertvector(v, bf16x2_t); return __builtin_bit_cast(unsigned, b); }
; DI void store_o_wide(bf16_t* rowp, const f32x16& o, float inv, int h) {
; #pragma unroll
;   for (int pr = 0; pr < 2; ++pr) {
;     const int g = 2 * pr;
;     const unsigned ax = pk2(o[4 * g] * inv, o[4 * g + 1] * inv), ay = pk2(o[4 * g + 2] * inv, o[4 * g + 3] * inv);
;     const unsigned bx = pk2(o[4 * g + 4] * inv, o[4 * g + 5] * inv), by = pk2(o[4 * g + 6] * inv, o[4 * g + 7] * inv);
;     const auto sx = __builtin_amdgcn_permlane32_swap(ax, bx, false, false);
;     const auto sy = __builtin_amdgcn_permlane32_swap(ay, by, false, false);
;     const u32x4 w = {sx[0], sy[0], sx[1], sy[1]};
;     *(u32x4*)(rowp + 8 * (g + h)) = w;
;   }
; }
; template <int TYPE, bool FIXREF>
; DI void attn_dense_unit(const Params& p, int layer, int head, int qb, char* lds, float bref) {
;     ...
;   lsum += ls0 + ls1 + ls2;
;   const float l = (NONES > 0 ? la[0] : 0.f) + lsum + __shfl_xor(lsum, 32);
;     ...
;   const float inv = 1.0f / l;
;   bf16_t* op = O + (size_t)q * 512 + head * 64;
;   store_o_wide(op, o0, inv, h); store_o_wide(op + 32, o1, inv, h);
	v_pk_add_f32 v[34:35], v[116:117], v[34:35]
	s_nop 0
	v_pk_add_f32 v[34:35], v[118:119], v[34:35]
	s_nop 0
	v_pk_add_f32 v[34:35], v[34:35], v[64:65]
	s_nop 0
	v_pk_add_f32 v[34:35], v[66:67], v[34:35]
	s_nop 0
	v_pk_add_f32 v[34:35], v[68:69], v[34:35]
	s_nop 0
	v_pk_add_f32 v[34:35], v[70:71], v[34:35]
	s_nop 0
	v_pk_add_f32 v[34:35], v[34:35], v[84:85]
	s_nop 0
	v_pk_add_f32 v[34:35], v[86:87], v[34:35]
	s_nop 0
	v_pk_add_f32 v[34:35], v[88:89], v[34:35]
	s_nop 0
	v_pk_add_f32 v[34:35], v[90:91], v[34:35]
	s_nop 0
	v_add_f32_e32 v33, v34, v35
	ds_bpermute_b32 v34, v199, v33
	v_add_f32_e32 v32, v33, v32
	s_waitcnt lgkmcnt(0)
	v_add_f32_e32 v32, v32, v34
	v_div_scale_f32 v33, s[0:1], v32, v32, 1.0
	v_rcp_f32_e32 v34, v33
	v_readlane_b32 s0, v253, 13
	v_readlane_b32 s1, v253, 14
	v_fma_f32 v35, -v33, v34, 1.0
	v_fmac_f32_e32 v34, v35, v34
	v_div_scale_f32 v35, vcc, 1.0, v32, 1.0
	v_mul_f32_e32 v36, v35, v34
	v_fma_f32 v37, -v33, v36, v35
	v_fmac_f32_e32 v36, v37, v34
	v_fma_f32 v33, -v33, v36, v35
	v_div_fmas_f32 v33, v33, v34, v36
	v_div_fixup_f32 v32, v33, v32, 1.0
	v_lshlrev_b64 v[34:35], 10, v[148:149]
	v_pk_mul_f32 v[16:17], v[16:17], v[32:33] op_sel_hi:[1,0]
	v_pk_mul_f32 v[18:19], v[18:19], v[32:33] op_sel_hi:[1,0]
	v_pk_mul_f32 v[0:1], v[0:1], v[32:33] op_sel_hi:[1,0]
	v_pk_mul_f32 v[2:3], v[2:3], v[32:33] op_sel_hi:[1,0]
	v_lshl_add_u64 v[34:35], s[0:1], 0, v[34:35]
	v_cvt_pk_bf16_f32 v16, v16, v17
	v_cvt_pk_bf16_f32 v17, v18, v19
	v_pk_mul_f32 v[18:19], v[20:21], v[32:33] op_sel_hi:[1,0]
	v_pk_mul_f32 v[20:21], v[22:23], v[32:33] op_sel_hi:[1,0]
	v_cvt_pk_bf16_f32 v0, v0, v1
	v_cvt_pk_bf16_f32 v1, v2, v3
	v_pk_mul_f32 v[2:3], v[4:5], v[32:33] op_sel_hi:[1,0]
	v_pk_mul_f32 v[4:5], v[6:7], v[32:33] op_sel_hi:[1,0]
	v_lshl_add_u64 v[34:35], v[34:35], 0, s[68:69]
	v_cvt_pk_bf16_f32 v18, v18, v19
	v_cvt_pk_bf16_f32 v19, v20, v21
	v_cvt_pk_bf16_f32 v2, v2, v3
	v_cvt_pk_bf16_f32 v3, v4, v5
	v_permlane32_swap_b32_e32 v16, v18
	v_permlane32_swap_b32_e32 v17, v19
	v_lshl_add_u64 v[20:21], v[34:35], 0, v[172:173]
	v_permlane32_swap_b32_e32 v0, v2
	v_permlane32_swap_b32_e32 v1, v3
	global_store_dwordx4 v[20:21], v[16:19], off
	global_store_dwordx4 v[20:21], v[0:3], off offset:64
	v_pk_mul_f32 v[22:23], v[30:31], v[32:33] op_sel_hi:[1,0]
	v_pk_mul_f32 v[16:17], v[24:25], v[32:33] op_sel_hi:[1,0]
	v_pk_mul_f32 v[18:19], v[26:27], v[32:33] op_sel_hi:[1,0]
	v_pk_mul_f32 v[0:1], v[8:9], v[32:33] op_sel_hi:[1,0]
	v_pk_mul_f32 v[2:3], v[10:11], v[32:33] op_sel_hi:[1,0]
	v_cvt_pk_bf16_f32 v16, v16, v17
	v_cvt_pk_bf16_f32 v17, v18, v19
	v_pk_mul_f32 v[18:19], v[28:29], v[32:33] op_sel_hi:[1,0]
	v_cvt_pk_bf16_f32 v0, v0, v1
	v_cvt_pk_bf16_f32 v1, v2, v3
	v_pk_mul_f32 v[2:3], v[12:13], v[32:33] op_sel_hi:[1,0]
	v_pk_mul_f32 v[6:7], v[14:15], v[32:33] op_sel_hi:[1,0]
	v_cvt_pk_bf16_f32 v18, v18, v19
	v_cvt_pk_bf16_f32 v19, v22, v23
	v_cvt_pk_bf16_f32 v2, v2, v3
	v_cvt_pk_bf16_f32 v3, v6, v7
	v_permlane32_swap_b32_e32 v16, v18
	v_permlane32_swap_b32_e32 v17, v19
	v_lshl_add_u64 v[4:5], v[20:21], 0, 64
	v_permlane32_swap_b32_e32 v0, v2
	v_permlane32_swap_b32_e32 v1, v3
	global_store_dwordx4 v[20:21], v[16:19], off offset:32

.LBB0_561:
	v_add_f32_e32 v34, v184, v34
	v_add_f32_e32 v35, v185, v35
	v_add_f32_e32 v36, v186, v36
	v_add_f32_e32 v37, v187, v37
	v_add_f32_e32 v32, v32, v34
	v_add_f32_e32 v33, v33, v35
	v_add_f32_e32 v36, v40, v36
	v_add_f32_e32 v37, v41, v37
	v_add_f32_e32 v32, v38, v32
	v_add_f32_e32 v33, v39, v33
	v_add_f32_e32 v36, v42, v36
	v_add_f32_e32 v37, v43, v37
	v_add_f32_e32 v32, v44, v32
	v_add_f32_e32 v33, v45, v33
	v_add_f32_e32 v36, v80, v36
	v_add_f32_e32 v37, v81, v37
	v_add_f32_e32 v32, v46, v32
	v_add_f32_e32 v33, v47, v33
	v_add_f32_e32 v36, v82, v36
	v_add_f32_e32 v37, v83, v37
	v_add_f32_e32 v32, v64, v32
	v_add_f32_e32 v33, v65, v33
	v_add_f32_e32 v36, v66, v36
	v_add_f32_e32 v37, v67, v37
	v_add_f32_e32 v32, v68, v32
	v_add_f32_e32 v33, v69, v33
	s_waitcnt lgkmcnt(0)
	s_barrier
	v_add_f32_e32 v184, v72, v32
	v_add_f32_e32 v185, v73, v33
	v_max_f32_e32 v32, v76, v76
	v_max_f32_e32 v33, v77, v77
	v_add_f32_e32 v36, v70, v36
	v_add_f32_e32 v37, v71, v37
	v_max_f32_e32 v32, v32, v33
	v_add_f32_e32 v186, v74, v36
	v_add_f32_e32 v187, v75, v37
	v_cmp_lt_f32_e32 vcc, s96, v32
	s_cbranch_vccz .LBB0_563
	v_max_f32_e32 v32, v32, v32
	v_max_f32_e32 v33, 0, v32
	v_exp_f32_e64 v34, -v33
	v_add_f32_e32 v209, v209, v33
	v_xor_b32_e32 v32, 0x80000000, v209
	v_sub_f32_e32 v127, v127, v33
	v_sub_f32_e32 v126, v126, v33
	v_sub_f32_e32 v125, v125, v33
	v_sub_f32_e32 v124, v124, v33
	v_sub_f32_e32 v123, v123, v33
	v_sub_f32_e32 v122, v122, v33
	v_sub_f32_e32 v121, v121, v33
	v_sub_f32_e32 v120, v120, v33
	v_sub_f32_e32 v119, v119, v33
	v_sub_f32_e32 v118, v118, v33
	v_sub_f32_e32 v117, v117, v33
	v_sub_f32_e32 v116, v116, v33
	v_sub_f32_e32 v115, v115, v33
	v_sub_f32_e32 v114, v114, v33
	v_sub_f32_e32 v113, v113, v33
	v_sub_f32_e32 v112, v112, v33
	v_sub_f32_e32 v111, v111, v33
	v_sub_f32_e32 v110, v110, v33
	v_sub_f32_e32 v109, v109, v33
	v_sub_f32_e32 v108, v108, v33
	v_sub_f32_e32 v107, v107, v33
	v_sub_f32_e32 v106, v106, v33
	v_sub_f32_e32 v105, v105, v33
	v_sub_f32_e32 v104, v104, v33
	v_sub_f32_e32 v103, v103, v33
	v_sub_f32_e32 v102, v102, v33
	v_sub_f32_e32 v101, v101, v33
	v_sub_f32_e32 v100, v100, v33
	v_sub_f32_e32 v99, v99, v33
	v_sub_f32_e32 v98, v98, v33
	v_sub_f32_e32 v97, v97, v33
	v_sub_f32_e32 v96, v96, v33
	v_pk_mul_f32 v[14:15], v[14:15], v[34:35] op_sel_hi:[1,0]
	v_pk_mul_f32 v[12:13], v[12:13], v[34:35] op_sel_hi:[1,0]
	v_pk_mul_f32 v[10:11], v[10:11], v[34:35] op_sel_hi:[1,0]
	v_pk_mul_f32 v[8:9], v[8:9], v[34:35] op_sel_hi:[1,0]
	v_pk_mul_f32 v[6:7], v[6:7], v[34:35] op_sel_hi:[1,0]
	v_pk_mul_f32 v[4:5], v[4:5], v[34:35] op_sel_hi:[1,0]
	v_pk_mul_f32 v[2:3], v[2:3], v[34:35] op_sel_hi:[1,0]
	v_pk_mul_f32 v[0:1], v[0:1], v[34:35] op_sel_hi:[1,0]
	v_pk_mul_f32 v[30:31], v[30:31], v[34:35] op_sel_hi:[1,0]
	v_pk_mul_f32 v[28:29], v[28:29], v[34:35] op_sel_hi:[1,0]
	v_pk_mul_f32 v[26:27], v[26:27], v[34:35] op_sel_hi:[1,0]
	v_pk_mul_f32 v[24:25], v[24:25], v[34:35] op_sel_hi:[1,0]
	v_pk_mul_f32 v[22:23], v[22:23], v[34:35] op_sel_hi:[1,0]
	v_pk_mul_f32 v[20:21], v[20:21], v[34:35] op_sel_hi:[1,0]
	v_pk_mul_f32 v[18:19], v[18:19], v[34:35] op_sel_hi:[1,0]
	v_pk_mul_f32 v[16:17], v[16:17], v[34:35] op_sel_hi:[1,0]
	v_pk_mul_f32 v[184:185], v[184:185], v[34:35] op_sel_hi:[1,0]
	v_pk_mul_f32 v[186:187], v[186:187], v[34:35] op_sel_hi:[1,0]
	v_mov_b32_e32 v33, v32
	v_mov_b32_e32 v34, v32
	v_mov_b32_e32 v35, v32
	v_mov_b32_e32 v36, v32
	v_mov_b32_e32 v37, v32
	v_mov_b32_e32 v38, v32
	v_mov_b32_e32 v39, v32
	v_mov_b32_e32 v40, v32
	v_mov_b32_e32 v41, v32
	v_mov_b32_e32 v42, v32
	v_mov_b32_e32 v43, v32
	v_mov_b32_e32 v44, v32
	v_mov_b32_e32 v45, v32
	v_mov_b32_e32 v46, v32
	v_mov_b32_e32 v47, v32
	v_mov_b32_e32 v48, v32
	v_mov_b32_e32 v49, v32
	v_mov_b32_e32 v50, v32
	v_mov_b32_e32 v51, v32
	v_mov_b32_e32 v52, v32
	v_mov_b32_e32 v53, v32
	v_mov_b32_e32 v54, v32
	v_mov_b32_e32 v55, v32
	v_mov_b32_e32 v56, v32
	v_mov_b32_e32 v57, v32
	v_mov_b32_e32 v58, v32
	v_mov_b32_e32 v59, v32
	v_mov_b32_e32 v60, v32
	v_mov_b32_e32 v61, v32
	v_mov_b32_e32 v62, v32
	v_mov_b32_e32 v63, v32
	s_branch .LBB0_564

.LBB0_570:
	v_add_f32_e32 v126, v186, v188
	v_add_f32_e32 v127, v187, v189
	v_add_f32_e32 v112, v112, v184
	v_add_f32_e32 v113, v113, v185
	v_add_f32_e32 v116, v116, v126
	v_add_f32_e32 v117, v117, v127
	v_add_f32_e32 v112, v114, v112
	v_add_f32_e32 v113, v115, v113
	v_add_f32_e32 v116, v190, v116
	v_add_f32_e32 v117, v191, v117
	v_add_f32_e32 v112, v118, v112
	v_add_f32_e32 v113, v119, v113
	v_add_f32_e32 v114, v122, v116
	v_add_f32_e32 v115, v123, v117
	s_waitcnt lgkmcnt(0)
	s_barrier
	v_add_f32_e32 v114, v124, v114
	v_add_f32_e32 v115, v125, v115
	s_nop 0
	v_add_f32_e32 v100, v100, v114
	v_add_f32_e32 v101, v101, v115
	v_add_f32_e32 v100, v104, v100
	v_add_f32_e32 v101, v105, v101
	v_add_f32_e32 v104, v120, v112
	v_add_f32_e32 v105, v121, v113
	v_add_f32_e32 v186, v108, v100
	v_add_f32_e32 v187, v109, v101
	v_add_f32_e32 v96, v96, v104
	v_add_f32_e32 v97, v97, v105
	v_add_f32_e32 v96, v98, v96
	v_add_f32_e32 v97, v99, v97
	v_add_f32_e32 v96, v102, v96
	v_add_f32_e32 v97, v103, v97
	v_add_f32_e32 v184, v106, v96
	v_add_f32_e32 v185, v107, v97
	v_max_f32_e32 v96, v110, v110
	v_max_f32_e32 v97, v111, v111
	v_max_f32_e32 v96, v96, v97
	v_cmp_lt_f32_e32 vcc, s96, v96
	s_cbranch_vccz .LBB0_572
	v_max_f32_e32 v32, v96, v96
	v_max_f32_e32 v33, 0, v32
	v_exp_f32_e64 v34, -v33
	v_add_f32_e32 v209, v209, v33
	v_xor_b32_e32 v32, 0x80000000, v209
	v_sub_f32_e32 v95, v95, v33
	v_sub_f32_e32 v94, v94, v33
	v_sub_f32_e32 v93, v93, v33
	v_sub_f32_e32 v92, v92, v33
	v_sub_f32_e32 v91, v91, v33
	v_sub_f32_e32 v90, v90, v33
	v_sub_f32_e32 v89, v89, v33
	v_sub_f32_e32 v88, v88, v33
	v_sub_f32_e32 v87, v87, v33
	v_sub_f32_e32 v86, v86, v33
	v_sub_f32_e32 v85, v85, v33
	v_sub_f32_e32 v84, v84, v33
	v_sub_f32_e32 v83, v83, v33
	v_sub_f32_e32 v82, v82, v33
	v_sub_f32_e32 v81, v81, v33
	v_sub_f32_e32 v80, v80, v33
	v_sub_f32_e32 v79, v79, v33
	v_sub_f32_e32 v78, v78, v33
	v_sub_f32_e32 v77, v77, v33
	v_sub_f32_e32 v76, v76, v33
	v_sub_f32_e32 v75, v75, v33
	v_sub_f32_e32 v74, v74, v33
	v_sub_f32_e32 v73, v73, v33
	v_sub_f32_e32 v72, v72, v33
	v_sub_f32_e32 v71, v71, v33
	v_sub_f32_e32 v70, v70, v33
	v_sub_f32_e32 v69, v69, v33
	v_sub_f32_e32 v68, v68, v33
	v_sub_f32_e32 v67, v67, v33
	v_sub_f32_e32 v66, v66, v33
	v_sub_f32_e32 v65, v65, v33
	v_sub_f32_e32 v64, v64, v33
	v_pk_mul_f32 v[14:15], v[14:15], v[34:35] op_sel_hi:[1,0]
	v_pk_mul_f32 v[12:13], v[12:13], v[34:35] op_sel_hi:[1,0]
	v_pk_mul_f32 v[10:11], v[10:11], v[34:35] op_sel_hi:[1,0]
	v_pk_mul_f32 v[8:9], v[8:9], v[34:35] op_sel_hi:[1,0]
	v_pk_mul_f32 v[6:7], v[6:7], v[34:35] op_sel_hi:[1,0]
	v_pk_mul_f32 v[4:5], v[4:5], v[34:35] op_sel_hi:[1,0]
	v_pk_mul_f32 v[2:3], v[2:3], v[34:35] op_sel_hi:[1,0]
	v_pk_mul_f32 v[0:1], v[0:1], v[34:35] op_sel_hi:[1,0]
	v_pk_mul_f32 v[30:31], v[30:31], v[34:35] op_sel_hi:[1,0]
	v_pk_mul_f32 v[28:29], v[28:29], v[34:35] op_sel_hi:[1,0]
	v_pk_mul_f32 v[26:27], v[26:27], v[34:35] op_sel_hi:[1,0]
	v_pk_mul_f32 v[24:25], v[24:25], v[34:35] op_sel_hi:[1,0]
	v_pk_mul_f32 v[22:23], v[22:23], v[34:35] op_sel_hi:[1,0]
	v_pk_mul_f32 v[20:21], v[20:21], v[34:35] op_sel_hi:[1,0]
	v_pk_mul_f32 v[18:19], v[18:19], v[34:35] op_sel_hi:[1,0]
	v_pk_mul_f32 v[16:17], v[16:17], v[34:35] op_sel_hi:[1,0]
	v_pk_mul_f32 v[184:185], v[184:185], v[34:35] op_sel_hi:[1,0]
	v_pk_mul_f32 v[186:187], v[186:187], v[34:35] op_sel_hi:[1,0]
	v_mov_b32_e32 v33, v32
	v_mov_b32_e32 v34, v32
	v_mov_b32_e32 v35, v32
	v_mov_b32_e32 v36, v32
	v_mov_b32_e32 v37, v32
	v_mov_b32_e32 v38, v32
	v_mov_b32_e32 v39, v32
	v_mov_b32_e32 v40, v32
	v_mov_b32_e32 v41, v32
	v_mov_b32_e32 v42, v32
	v_mov_b32_e32 v43, v32
	v_mov_b32_e32 v44, v32
	v_mov_b32_e32 v45, v32
	v_mov_b32_e32 v46, v32
	v_mov_b32_e32 v47, v32
	v_mov_b32_e32 v48, v32
	v_mov_b32_e32 v49, v32
	v_mov_b32_e32 v50, v32
	v_mov_b32_e32 v51, v32
	v_mov_b32_e32 v52, v32
	v_mov_b32_e32 v53, v32
	v_mov_b32_e32 v54, v32
	v_mov_b32_e32 v55, v32
	v_mov_b32_e32 v56, v32
	v_mov_b32_e32 v57, v32
	v_mov_b32_e32 v58, v32
	v_mov_b32_e32 v59, v32
	v_mov_b32_e32 v60, v32
	v_mov_b32_e32 v61, v32
	v_mov_b32_e32 v62, v32
	v_mov_b32_e32 v63, v32

.LBB0_578:
	v_add_f32_e32 v80, v80, v184
	v_add_f32_e32 v81, v81, v185
	v_add_f32_e32 v94, v186, v188
	v_add_f32_e32 v95, v187, v189
	v_add_f32_e32 v80, v82, v80
	v_add_f32_e32 v81, v83, v81
	v_add_f32_e32 v94, v190, v94
	v_add_f32_e32 v95, v191, v95
	v_add_f32_e32 v80, v84, v80
	v_add_f32_e32 v81, v85, v81
	v_add_f32_e32 v86, v86, v94
	v_add_f32_e32 v87, v87, v95
	v_add_f32_e32 v80, v88, v80
	v_add_f32_e32 v81, v89, v81
	v_add_f32_e32 v86, v90, v86
	v_add_f32_e32 v87, v91, v87
	v_add_f32_e32 v64, v64, v80
	v_add_f32_e32 v65, v65, v81
	v_add_f32_e32 v86, v92, v86
	v_add_f32_e32 v87, v93, v87
	v_add_f32_e32 v64, v66, v64
	v_add_f32_e32 v65, v67, v65
	v_add_f32_e32 v68, v68, v86
	v_add_f32_e32 v69, v69, v87
	v_add_f32_e32 v64, v70, v64
	v_add_f32_e32 v65, v71, v65
	s_waitcnt lgkmcnt(0)
	s_barrier
	v_add_f32_e32 v184, v74, v64
	v_add_f32_e32 v185, v75, v65
	v_max_f32_e32 v64, v78, v78
	v_max_f32_e32 v65, v79, v79
	v_add_f32_e32 v68, v72, v68
	v_add_f32_e32 v69, v73, v69
	v_max_f32_e32 v64, v64, v65
	v_add_f32_e32 v186, v76, v68
	v_add_f32_e32 v187, v77, v69
	v_cmp_lt_f32_e32 vcc, s96, v64
	s_cbranch_vccz .LBB0_580
	v_max_f32_e32 v32, v64, v64
	v_max_f32_e32 v33, 0, v32
	v_exp_f32_e64 v34, -v33
	v_add_f32_e32 v209, v209, v33
	v_xor_b32_e32 v32, 0x80000000, v209
	v_sub_f32_e32 v127, v127, v33
	v_sub_f32_e32 v126, v126, v33
	v_sub_f32_e32 v125, v125, v33
	v_sub_f32_e32 v124, v124, v33
	v_sub_f32_e32 v123, v123, v33
	v_sub_f32_e32 v122, v122, v33
	v_sub_f32_e32 v121, v121, v33
	v_sub_f32_e32 v120, v120, v33
	v_sub_f32_e32 v119, v119, v33
	v_sub_f32_e32 v118, v118, v33
	v_sub_f32_e32 v117, v117, v33
	v_sub_f32_e32 v116, v116, v33
	v_sub_f32_e32 v115, v115, v33
	v_sub_f32_e32 v114, v114, v33
	v_sub_f32_e32 v113, v113, v33
	v_sub_f32_e32 v112, v112, v33
	v_sub_f32_e32 v111, v111, v33
	v_sub_f32_e32 v110, v110, v33
	v_sub_f32_e32 v109, v109, v33
	v_sub_f32_e32 v108, v108, v33
	v_sub_f32_e32 v107, v107, v33
	v_sub_f32_e32 v106, v106, v33
	v_sub_f32_e32 v105, v105, v33
	v_sub_f32_e32 v104, v104, v33
	v_sub_f32_e32 v103, v103, v33
	v_sub_f32_e32 v102, v102, v33
	v_sub_f32_e32 v101, v101, v33
	v_sub_f32_e32 v100, v100, v33
	v_sub_f32_e32 v99, v99, v33
	v_sub_f32_e32 v98, v98, v33
	v_sub_f32_e32 v97, v97, v33
	v_sub_f32_e32 v96, v96, v33
	v_pk_mul_f32 v[14:15], v[14:15], v[34:35] op_sel_hi:[1,0]
	v_pk_mul_f32 v[12:13], v[12:13], v[34:35] op_sel_hi:[1,0]
	v_pk_mul_f32 v[10:11], v[10:11], v[34:35] op_sel_hi:[1,0]
	v_pk_mul_f32 v[8:9], v[8:9], v[34:35] op_sel_hi:[1,0]
	v_pk_mul_f32 v[6:7], v[6:7], v[34:35] op_sel_hi:[1,0]
	v_pk_mul_f32 v[4:5], v[4:5], v[34:35] op_sel_hi:[1,0]
	v_pk_mul_f32 v[2:3], v[2:3], v[34:35] op_sel_hi:[1,0]
	v_pk_mul_f32 v[0:1], v[0:1], v[34:35] op_sel_hi:[1,0]
	v_pk_mul_f32 v[30:31], v[30:31], v[34:35] op_sel_hi:[1,0]
	v_pk_mul_f32 v[28:29], v[28:29], v[34:35] op_sel_hi:[1,0]
	v_pk_mul_f32 v[26:27], v[26:27], v[34:35] op_sel_hi:[1,0]
	v_pk_mul_f32 v[24:25], v[24:25], v[34:35] op_sel_hi:[1,0]
	v_pk_mul_f32 v[22:23], v[22:23], v[34:35] op_sel_hi:[1,0]
	v_pk_mul_f32 v[20:21], v[20:21], v[34:35] op_sel_hi:[1,0]
	v_pk_mul_f32 v[18:19], v[18:19], v[34:35] op_sel_hi:[1,0]
	v_pk_mul_f32 v[16:17], v[16:17], v[34:35] op_sel_hi:[1,0]
	v_pk_mul_f32 v[184:185], v[184:185], v[34:35] op_sel_hi:[1,0]
	v_pk_mul_f32 v[186:187], v[186:187], v[34:35] op_sel_hi:[1,0]
	v_mov_b32_e32 v33, v32
	v_mov_b32_e32 v34, v32
	v_mov_b32_e32 v35, v32
	v_mov_b32_e32 v36, v32
	v_mov_b32_e32 v37, v32
	v_mov_b32_e32 v38, v32
	v_mov_b32_e32 v39, v32
	v_mov_b32_e32 v40, v32
	v_mov_b32_e32 v41, v32
	v_mov_b32_e32 v42, v32
	v_mov_b32_e32 v43, v32
	v_mov_b32_e32 v44, v32
	v_mov_b32_e32 v45, v32
	v_mov_b32_e32 v46, v32
	v_mov_b32_e32 v47, v32
	v_mov_b32_e32 v48, v32
	v_mov_b32_e32 v49, v32
	v_mov_b32_e32 v50, v32
	v_mov_b32_e32 v51, v32
	v_mov_b32_e32 v52, v32
	v_mov_b32_e32 v53, v32
	v_mov_b32_e32 v54, v32
	v_mov_b32_e32 v55, v32
	v_mov_b32_e32 v56, v32
	v_mov_b32_e32 v57, v32
	v_mov_b32_e32 v58, v32
	v_mov_b32_e32 v59, v32
	v_mov_b32_e32 v60, v32
	v_mov_b32_e32 v61, v32
	v_mov_b32_e32 v62, v32
	v_mov_b32_e32 v63, v32

.LBB0_586:
	v_add_f32_e32 v166, v186, v166
	v_add_f32_e32 v167, v187, v167
	s_waitcnt lgkmcnt(0)
	s_barrier
	v_add_f32_e32 v166, v168, v166
	v_add_f32_e32 v167, v169, v167
	s_nop 0
	v_add_f32_e32 v120, v120, v166
	v_add_f32_e32 v121, v121, v167
	v_add_f32_e32 v120, v122, v120
	v_add_f32_e32 v121, v123, v121
	v_add_f32_e32 v120, v124, v120
	v_add_f32_e32 v121, v125, v121
	v_add_f32_e32 v100, v100, v120
	v_add_f32_e32 v101, v101, v121
	v_add_f32_e32 v100, v104, v100
	v_add_f32_e32 v101, v105, v101
	v_add_f32_e32 v104, v112, v184
	v_add_f32_e32 v105, v113, v185
	v_add_f32_e32 v186, v108, v100
	v_add_f32_e32 v187, v109, v101
	v_add_f32_e32 v104, v114, v104
	v_add_f32_e32 v105, v115, v105
	v_add_f32_e32 v104, v116, v104
	v_add_f32_e32 v105, v117, v105
	v_add_f32_e32 v104, v118, v104
	v_add_f32_e32 v105, v119, v105
	v_add_f32_e32 v96, v96, v104
	v_add_f32_e32 v97, v97, v105
	v_add_f32_e32 v96, v98, v96
	v_add_f32_e32 v97, v99, v97
	v_add_f32_e32 v96, v102, v96
	v_add_f32_e32 v97, v103, v97
	v_add_f32_e32 v184, v106, v96
	v_add_f32_e32 v185, v107, v97
	v_max_f32_e32 v96, v110, v110
	v_max_f32_e32 v97, v111, v111
	v_max_f32_e32 v96, v96, v97
	v_cmp_lt_f32_e32 vcc, s96, v96
	s_cbranch_vccz .LBB0_554
	v_max_f32_e32 v32, v96, v96
	v_max_f32_e32 v33, 0, v32
	v_exp_f32_e64 v34, -v33
	v_add_f32_e32 v209, v209, v33
	v_xor_b32_e32 v32, 0x80000000, v209
	v_sub_f32_e32 v95, v95, v33
	v_sub_f32_e32 v94, v94, v33
	v_sub_f32_e32 v93, v93, v33
	v_sub_f32_e32 v92, v92, v33
	v_sub_f32_e32 v91, v91, v33
	v_sub_f32_e32 v90, v90, v33
	v_sub_f32_e32 v89, v89, v33
	v_sub_f32_e32 v88, v88, v33
	v_sub_f32_e32 v87, v87, v33
	v_sub_f32_e32 v86, v86, v33
	v_sub_f32_e32 v85, v85, v33
	v_sub_f32_e32 v84, v84, v33
	v_sub_f32_e32 v83, v83, v33
	v_sub_f32_e32 v82, v82, v33
	v_sub_f32_e32 v81, v81, v33
	v_sub_f32_e32 v80, v80, v33
	v_sub_f32_e32 v79, v79, v33
	v_sub_f32_e32 v78, v78, v33
	v_sub_f32_e32 v77, v77, v33
	v_sub_f32_e32 v76, v76, v33
	v_sub_f32_e32 v75, v75, v33
	v_sub_f32_e32 v74, v74, v33
	v_sub_f32_e32 v73, v73, v33
	v_sub_f32_e32 v72, v72, v33
	v_sub_f32_e32 v71, v71, v33
	v_sub_f32_e32 v70, v70, v33
	v_sub_f32_e32 v69, v69, v33
	v_sub_f32_e32 v68, v68, v33
	v_sub_f32_e32 v67, v67, v33
	v_sub_f32_e32 v66, v66, v33
	v_sub_f32_e32 v65, v65, v33
	v_sub_f32_e32 v64, v64, v33
	v_pk_mul_f32 v[14:15], v[14:15], v[34:35] op_sel_hi:[1,0]
	v_pk_mul_f32 v[12:13], v[12:13], v[34:35] op_sel_hi:[1,0]
	v_pk_mul_f32 v[10:11], v[10:11], v[34:35] op_sel_hi:[1,0]
	v_pk_mul_f32 v[8:9], v[8:9], v[34:35] op_sel_hi:[1,0]
	v_pk_mul_f32 v[6:7], v[6:7], v[34:35] op_sel_hi:[1,0]
	v_pk_mul_f32 v[4:5], v[4:5], v[34:35] op_sel_hi:[1,0]
	v_pk_mul_f32 v[2:3], v[2:3], v[34:35] op_sel_hi:[1,0]
	v_pk_mul_f32 v[0:1], v[0:1], v[34:35] op_sel_hi:[1,0]
	v_pk_mul_f32 v[30:31], v[30:31], v[34:35] op_sel_hi:[1,0]
	v_pk_mul_f32 v[28:29], v[28:29], v[34:35] op_sel_hi:[1,0]
	v_pk_mul_f32 v[26:27], v[26:27], v[34:35] op_sel_hi:[1,0]
	v_pk_mul_f32 v[24:25], v[24:25], v[34:35] op_sel_hi:[1,0]
	v_pk_mul_f32 v[22:23], v[22:23], v[34:35] op_sel_hi:[1,0]
	v_pk_mul_f32 v[20:21], v[20:21], v[34:35] op_sel_hi:[1,0]
	v_pk_mul_f32 v[18:19], v[18:19], v[34:35] op_sel_hi:[1,0]
	v_pk_mul_f32 v[16:17], v[16:17], v[34:35] op_sel_hi:[1,0]
	v_pk_mul_f32 v[184:185], v[184:185], v[34:35] op_sel_hi:[1,0]
	v_pk_mul_f32 v[186:187], v[186:187], v[34:35] op_sel_hi:[1,0]
	v_mov_b32_e32 v33, v32
	v_mov_b32_e32 v34, v32
	v_mov_b32_e32 v35, v32
	v_mov_b32_e32 v36, v32
	v_mov_b32_e32 v37, v32
	v_mov_b32_e32 v38, v32
	v_mov_b32_e32 v39, v32
	v_mov_b32_e32 v40, v32
	v_mov_b32_e32 v41, v32
	v_mov_b32_e32 v42, v32
	v_mov_b32_e32 v43, v32
	v_mov_b32_e32 v44, v32
	v_mov_b32_e32 v45, v32
	v_mov_b32_e32 v46, v32
	v_mov_b32_e32 v47, v32
	v_mov_b32_e32 v48, v32
	v_mov_b32_e32 v49, v32
	v_mov_b32_e32 v50, v32
	v_mov_b32_e32 v51, v32
	v_mov_b32_e32 v52, v32
	v_mov_b32_e32 v53, v32
	v_mov_b32_e32 v54, v32
	v_mov_b32_e32 v55, v32
	v_mov_b32_e32 v56, v32
	v_mov_b32_e32 v57, v32
	v_mov_b32_e32 v58, v32
	v_mov_b32_e32 v59, v32
	v_mov_b32_e32 v60, v32
	v_mov_b32_e32 v61, v32
	v_mov_b32_e32 v62, v32
	v_mov_b32_e32 v63, v32
	s_branch .LBB0_554
